# GEMM mainloops: one barrier event per LOAD+MMA period (leading half barriers after MMA, trailing half after LOAD) with static s_setprio (trailing half 2, leading half 1) replacing per-segment flips
# speedup vs baseline: 1.0069x; 1.0051x over previous
; __device__ __forceinline__ int opaque_tid() { int t = threadIdx.x; asm volatile("" : "+v"(t)); return t; }
; #define PG8_BAR __builtin_amdgcn_s_barrier()
; template <class Epi, class Sched, bool ALIGN_EPI = false, bool SP2 = false>
; __device__ __forceinline__ void gemm_phase(PG8_LAS unsigned char* lds, const Gemm g, const Sched& S, const Epi& E) {
;     const int tid = opaque_tid(), wid = __builtin_amdgcn_readfirstlane(tid >> 6), lane = tid & 63, wr = wid >> 2, wc = wid & 3, fr = lane & 15, fq = lane >> 4;
;     const int K = g.K, nt = K / BK;
;     unsigned voffA[2], voffB[2];
; #pragma unroll
;     for (int i = 0; i < 2; ++i) { int R, C; stage_rc(tid * 16 + i * 8192, R, C); const int Rb = Epi::PERM ? ((R & ~31) + perm32(R & 31)) : R;
;         voffA[i] = (unsigned)(R * K + C) * 2u; voffB[i] = (unsigned)(Rb * K + C) * 2u; }
;     const size_t kstep = (size_t)(BK * 2);
;     const size_t hstep = (size_t)HALF * K * 2;
;     const size_t tstep = 2 * hstep;
;     const unsigned ldsw = (unsigned)wid * 1024u;
;     const int aoff = lds_byte(wr * 64 + fr, fq * 8), boff = lds_byte(wc * 32 + fr, fq * 8);
;     ...
;     Unit cur, nxt; int ui = 0;
;     if (!S.next(0, cur)) return;
;     f32x4 acc[2][2][4][2];
; #pragma unroll
;     for (int a = 0; a < 2; ++a)
; #pragma unroll
;         for (int b = 0; b < 2; ++b)
; #pragma unroll
;             for (int m = 0; m < 4; ++m)
; #pragma unroll
;                 for (int n = 0; n < 2; ++n) acc[a][b][m][n] = (f32x4){0.f, 0.f, 0.f, 0.f};
;     bf16x8 At[4][2], B0[2][2], B1[2][2];
;     const char* cA = (const char*)g.A + (size_t)cur.pm * tstep; const char* cB = (const char*)g.Bt + (size_t)cur.pn * tstep;
;     S.a_ready(cur);
;     if constexpr (SP2) {
;         PG8_STAGE(PG8_SB(0, 0), cB, voffB); PG8_STAGE(PG8_SB(0, 1), cB + hstep, voffB); PG8_STAGE(PG8_SA(0, 0), cA, voffA); PG8_STAGE(PG8_SA(0, 1), cA + hstep, voffA);
;         if (wr == 1) PG8_BAR;
;         PG8_WAIT_V(2); PG8_BAR;
;         PG8_STAGE(PG8_SB(1, 0), cB + kstep, voffB); PG8_STAGE(PG8_SA(1, 0), cA + kstep, voffA); PG8_STAGE(PG8_SB(1, 1), cB + hstep + kstep, voffB);
;         PG8_WAIT_V(6); PG8_BAR;
;     } else {
;         PG8_STAGE(PG8_SB(0, 0), cB, voffB); PG8_STAGE(PG8_SA(0, 0), cA, voffA); PG8_STAGE(PG8_SB(0, 1), cB + hstep, voffB); PG8_STAGE(PG8_SA(0, 1), cA + hstep, voffA);
;         if (wr == 1) PG8_BAR;
;         PG8_WAIT_V(4); PG8_BAR;
.LBB0_81:
	v_readlane_b32 s6, v244, 45
	v_readlane_b32 s7, v244, 46
	s_andn2_b64 vcc, exec, s[6:7]
	s_cbranch_vccnz .LBB0_122
	v_ashrrev_i32_e32 v1, 31, v11
	v_lshrrev_b32_e32 v1, 26, v1
	v_add_u32_e32 v1, v11, v1
	v_ashrrev_i32_e32 v8, 6, v1
	v_bfe_i32 v1, v11, 27, 1
	v_lshlrev_b32_e32 v0, 4, v11
	v_lshrrev_b32_e32 v1, 22, v1
	v_add_u32_e32 v1, v0, v1
	v_and_b32_e32 v1, 0xfffffc00, v1
	v_sub_u32_e32 v1, v0, v1
	v_lshrrev_b32_e32 v2, 4, v1
	v_bitop3_b32 v2, v2, v1, 32 bitop3:0x6c
	v_ashrrev_i32_e32 v1, 31, v1
	v_lshrrev_b32_e32 v1, 26, v1
	v_add_u32_e32 v1, v2, v1
	v_ashrrev_i32_e32 v9, 6, v1
	v_lshlrev_b32_e32 v3, 3, v8
	v_mul_i32_i24_e32 v4, 64, v9
	v_and_b32_e32 v3, -16, v3
	v_sub_u32_e32 v2, v2, v4
	v_add_u32_e32 v1, v9, v3
	v_lshlrev_b32_e32 v3, 5, v8
	v_ashrrev_i16_sdwa v2, v205, sext(v2) dst_sel:DWORD dst_unused:UNUSED_PAD src0_sel:DWORD src1_sel:BYTE_0
	v_and_b32_e32 v3, 32, v3
	v_bfe_i32 v10, v2, 0, 16
	v_and_b32_e32 v5, 3, v9
	s_mov_b32 s5, 0x1fffe0
	v_add_lshl_u32 v3, v3, v10, 1
	v_add_u32_e32 v0, 0x2000, v0
	v_lshlrev_b32_e32 v2, 1, v1
	v_lshrrev_b32_e32 v4, 2, v1
	v_and_or_b32 v5, v1, s5, v5
	v_lshl_add_u32 v186, v1, 11, v3
	v_ashrrev_i32_e32 v1, 31, v0
	v_lshrrev_b32_e32 v1, 22, v1
	v_add_u32_e32 v1, v0, v1
	v_ashrrev_i32_e32 v12, 10, v1
	v_mul_i32_i24_e32 v1, 0x400, v12
	v_sub_u32_e32 v0, v0, v1
	v_and_b32_e32 v2, 24, v2
	v_and_b32_e32 v4, 4, v4
	v_lshrrev_b32_e32 v1, 4, v0
	v_or3_b32 v2, v5, v4, v2
	v_bitop3_b32 v0, v1, v0, 32 bitop3:0x6c
	v_lshl_add_u32 v188, v2, 11, v3
	v_ashrrev_i32_e32 v2, 31, v0
	v_lshrrev_b32_e32 v2, 26, v2
	v_lshlrev_b32_e32 v1, 3, v12
	v_add_u32_e32 v2, v0, v2
	v_and_b32_e32 v1, -16, v1
	v_ashrrev_i32_e32 v13, 6, v2
	v_add_u32_e32 v1, v13, v1
	v_and_b32_e32 v4, 3, v13
	v_and_b32_e32 v2, 0xc0, v2
	v_and_or_b32 v4, v1, s5, v4
	s_ashr_i32 s5, s4, 6
	s_ashr_i32 s63, s62, 31
	s_ashr_i32 s59, s58, 31
	s_ashr_i32 s6, s4, 8
	v_sub_u32_e32 v0, v0, v2
	s_lshl_b32 s44, s5, 10
	s_lshl_b64 s[8:9], s[62:63], 19
	s_lshl_b64 s[10:11], s[58:59], 19
	v_readlane_b32 s7, v243, 27
	v_ashrrev_i16_sdwa v0, v205, sext(v0) dst_sel:DWORD dst_unused:UNUSED_PAD src0_sel:DWORD src1_sel:BYTE_0
	s_add_u32 s10, s7, s10
	v_readlane_b32 s7, v243, 28
	v_lshlrev_b32_e32 v3, 5, v12
	v_bfe_i32 v14, v0, 0, 16
	v_lshlrev_b32_e32 v0, 1, v1
	v_lshrrev_b32_e32 v2, 2, v1
	s_addc_u32 s11, s7, s11
	s_add_i32 s52, s44, 0
	v_and_b32_e32 v3, 32, v3
	v_and_b32_e32 v0, 24, v0
	v_and_b32_e32 v2, 4, v2
	s_add_i32 m0, s52, 0x10000
	v_or3_b32 v0, v4, v2, v0
	v_add_lshl_u32 v2, v3, v14, 1
	global_load_lds_dwordx4 v188, s[10:11]
	s_add_i32 m0, s52, 0x12000
	v_lshl_add_u32 v192, v0, 11, v2
	s_add_u32 s12, s10, 0x40000
	global_load_lds_dwordx4 v192, s[10:11]
	s_addc_u32 s13, s11, 0
	s_add_i32 m0, s52, 0x14000
	v_lshl_add_u32 v190, v1, 11, v2
	global_load_lds_dwordx4 v188, s[12:13]
	s_add_i32 m0, s52, 0x16000
	s_add_u32 s8, s40, s8
	s_addc_u32 s9, s41, s9
	s_add_i32 s53, s52, 0x2000
	global_load_lds_dwordx4 v192, s[12:13]
	s_mov_b32 m0, s52
	s_add_u32 s12, s8, 0x40000
	global_load_lds_dwordx4 v186, s[8:9]
	s_mov_b32 m0, s53
	s_addc_u32 s13, s9, 0
	s_add_i32 s59, s52, 0x4000
	global_load_lds_dwordx4 v190, s[8:9]
	s_mov_b32 m0, s59
	s_add_i32 s60, s52, 0x6000
	global_load_lds_dwordx4 v186, s[12:13]
	s_mov_b32 m0, s60
	v_writelane_b32 v242, s20, 7
	global_load_lds_dwordx4 v190, s[12:13]
	s_nop 0
	v_writelane_b32 v242, s21, 8
	v_mov_b32_e32 v189, v48
	v_mov_b32_e32 v193, v48
	v_mov_b32_e32 v187, v48
	v_mov_b32_e32 v191, v48
	s_cmp_eq_u32 s6, 1
	v_writelane_b32 v242, s91, 9
	s_mov_b32 s73, s51
	v_lshl_add_u64 v[6:7], s[10:11], 0, v[188:189]
	v_lshl_add_u64 v[4:5], s[10:11], 0, v[192:193]
	v_lshl_add_u64 v[0:1], s[8:9], 0, v[186:187]
	s_cselect_b64 s[18:19], -1, 0
	s_cmp_lg_u32 s6, 1
	v_lshl_add_u64 v[2:3], s[8:9], 0, v[190:191]
	v_writelane_b32 v242, s76, 10
	s_setprio 1
	s_cbranch_scc1 .LBB0_84
	s_setprio 2

; #define PG8_STAGE(bufoff, gbase, voff) do { _Pragma("unroll") for (int _i = 0; _i < 2; ++_i) \
;         __builtin_amdgcn_global_load_lds((const unsigned*)((const char*)(gbase) + (voff)[_i]), (PG8_LAS unsigned*)(lds + (bufoff) + ldsw + _i * 8192), 16, 0, 0); } while (0)
; #define PG8_LDA(dst, b, h) do { _Pragma("unroll") for (int m = 0; m < 4; ++m) _Pragma("unroll") for (int k = 0; k < 2; ++k) dst[m][k] = *(const PG8_LAS bf16x8*)(lds + PG8_SA(b, h) + aoff + m * 2048 + k * 1024); } while (0)
; #define PG8_LDB(dst, b, h) do { _Pragma("unroll") for (int n = 0; n < 2; ++n) _Pragma("unroll") for (int k = 0; k < 2; ++k) dst[n][k] = *(const PG8_LAS bf16x8*)(lds + PG8_SB(b, h) + boff + n * 2048 + k * 1024); } while (0)
; #define PG8_MMA(ai, bj, At, Bt) do { __builtin_amdgcn_s_setprio(1); _Pragma("unroll") for (int m = 0; m < 4; ++m) _Pragma("unroll") for (int n = 0; n < 2; ++n) _Pragma("unroll") for (int k = 0; k < 2; ++k) \
;         acc[ai][bj][m][n] = mma16<Epi::F16>(Bt[n][k], At[m][k], acc[ai][bj][m][n]); __builtin_amdgcn_s_setprio(0); } while (0)
; #define PG8_WAIT_V(n) asm volatile("s_waitcnt vmcnt(" #n ")" ::: "memory")
; #define PG8_WAIT_L(n) asm volatile("s_waitcnt lgkmcnt(" #n ")" ::: "memory")
; #define PG8_BAR __builtin_amdgcn_s_barrier()
; #define PG8_SCHED __builtin_amdgcn_sched_barrier(0)
; template <class Epi, class Sched, bool ALIGN_EPI = false, bool SP2 = false>
; __device__ __forceinline__ void gemm_phase(PG8_LAS unsigned char* lds, const Gemm g, const Sched& S, const Epi& E) {
;     ...
;             PG8_LDB(B0, 0, 0); PG8_LDB(B1, 0, 1); PG8_SCHED; PG8_LDA(At, 0, 0); PG8_STAGE(PG8_SA(1, 1), a1 + hstep, voffA);
;             PG8_WAIT_V(8); PG8_WAIT_L(0); PG8_BAR; PG8_MMA(0, 0, At, B0); PG8_MMA(0, 1, At, B1); PG8_BAR; PG8_SCHED;
;             PG8_LDA(At, 0, 1); PG8_STAGE(PG8_SB(0, 0), b2, voffB); PG8_STAGE(PG8_SB(0, 1), b2 + hstep, voffB); PG8_STAGE(PG8_SA(0, 0), a2, voffA);
.LBB0_92:
	s_add_u32 s10, s8, 0xfffc0080
	s_addc_u32 s11, s9, -1
	s_add_i32 s14, 0, 0x10000
	s_cmp_eq_u32 vcc_lo, 12
	s_cselect_b32 s65, s35, s11
	s_cselect_b32 s64, s96, s10
	v_add_u32_e32 v102, s14, v185
	s_cselect_b32 s11, s31, s99
	s_cselect_b32 s10, s97, s98
	s_add_i32 vcc_hi, 0, 0x14000
	ds_read_b128 v[128:131], v102
	ds_read_b128 v[132:135], v102 offset:1024
	ds_read_b128 v[136:139], v102 offset:2048
	ds_read_b128 v[140:143], v102 offset:3072
	v_add_u32_e32 v102, vcc_hi, v185
	ds_read_b128 v[144:147], v102
	ds_read_b128 v[148:151], v102 offset:1024
	ds_read_b128 v[152:155], v102 offset:2048
	ds_read_b128 v[156:159], v102 offset:3072
	v_lshl_add_u64 v[102:103], s[8:9], 0, v[198:199]
	s_add_i32 m0, s52, 0xc000
	ds_read_b128 v[168:171], v209
	ds_read_b128 v[172:175], v209 offset:1024
	ds_read_b128 v[176:179], v209 offset:2048
	ds_read_b128 v[180:183], v209 offset:3072
	ds_read_b128 v[212:215], v209 offset:4096
	ds_read_b128 v[216:219], v209 offset:5120
	ds_read_b128 v[220:223], v209 offset:6144
	ds_read_b128 v[224:227], v209 offset:7168
	global_load_lds_dwordx4 v[102:103], off
	v_lshl_add_u64 v[102:103], s[8:9], 0, v[200:201]
	s_add_i32 m0, s52, 0xe000
	s_nop 0
	global_load_lds_dwordx4 v[102:103], off
	s_waitcnt vmcnt(8)
	s_waitcnt lgkmcnt(0)
	s_cmp_lg_u64 s[18:19], 0
	s_cbranch_scc0 .Lmy_b1_0_0
	s_barrier
.Lmy_b1_0_0:
	s_waitcnt lgkmcnt(0)
	v_mfma_f32_16x16x32_f16 v[164:167], v[128:131], v[168:171], v[164:167]
	v_mfma_f32_16x16x32_f16 v[62:65], v[136:139], v[168:171], v[62:65]
	v_mfma_f32_16x16x32_f16 v[124:127], v[128:131], v[176:179], v[124:127]
	v_mfma_f32_16x16x32_f16 v[54:57], v[136:139], v[176:179], v[54:57]
	v_mfma_f32_16x16x32_f16 v[114:117], v[128:131], v[212:215], v[114:117]
	v_mfma_f32_16x16x32_f16 v[44:47], v[136:139], v[212:215], v[44:47]
	v_mfma_f32_16x16x32_f16 v[108:111], v[128:131], v[220:223], v[110:113]
	v_mfma_f32_16x16x32_f16 v[40:43], v[136:139], v[220:223], v[40:43]
	v_mfma_f32_16x16x32_f16 v[164:167], v[132:135], v[172:175], v[164:167]
	v_mfma_f32_16x16x32_f16 v[62:65], v[140:143], v[172:175], v[62:65]
	v_mfma_f32_16x16x32_f16 v[124:127], v[132:135], v[180:183], v[124:127]
	v_mfma_f32_16x16x32_f16 v[54:57], v[140:143], v[180:183], v[54:57]
	v_mfma_f32_16x16x32_f16 v[114:117], v[132:135], v[216:219], v[114:117]
	v_mfma_f32_16x16x32_f16 v[44:47], v[140:143], v[216:219], v[44:47]
	v_mfma_f32_16x16x32_f16 v[108:111], v[132:135], v[224:227], v[108:111]
	v_mfma_f32_16x16x32_f16 v[40:43], v[140:143], v[224:227], v[40:43]
	v_mfma_f32_16x16x32_f16 v[160:163], v[144:147], v[168:171], v[160:163]
	v_mfma_f32_16x16x32_f16 v[58:61], v[152:155], v[168:171], v[58:61]
	v_mfma_f32_16x16x32_f16 v[118:121], v[144:147], v[176:179], v[120:123]
	v_mfma_f32_16x16x32_f16 v[50:53], v[152:155], v[176:179], v[50:53]
	v_mfma_f32_16x16x32_f16 v[102:105], v[144:147], v[212:215], v[104:107]
	v_mfma_f32_16x16x32_f16 v[36:39], v[152:155], v[212:215], v[36:39]
	v_mfma_f32_16x16x32_f16 v[98:101], v[144:147], v[220:223], v[98:101]
	v_mfma_f32_16x16x32_f16 v[32:35], v[152:155], v[220:223], v[32:35]
	v_mfma_f32_16x16x32_f16 v[160:163], v[148:151], v[172:175], v[160:163]
	v_mfma_f32_16x16x32_f16 v[58:61], v[156:159], v[172:175], v[58:61]
	v_mfma_f32_16x16x32_f16 v[118:121], v[148:151], v[180:183], v[118:121]
	v_mfma_f32_16x16x32_f16 v[50:53], v[156:159], v[180:183], v[50:53]
	v_mfma_f32_16x16x32_f16 v[102:105], v[148:151], v[216:219], v[102:105]
	v_mfma_f32_16x16x32_f16 v[36:39], v[156:159], v[216:219], v[36:39]
	v_mfma_f32_16x16x32_f16 v[98:101], v[148:151], v[224:227], v[98:101]
	v_mfma_f32_16x16x32_f16 v[32:35], v[156:159], v[224:227], v[32:35]
	s_cmp_lg_u64 s[18:19], 0
	s_cbranch_scc1 .Lmy_b2_0_0
	s_barrier
.Lmy_b2_0_0:
	s_add_i32 s14, s14, s44
	v_lshl_add_u64 v[228:229], s[10:11], 0, v[188:189]
	s_mov_b32 m0, s14
	ds_read_b128 v[168:171], v209 offset:16384
	ds_read_b128 v[172:175], v209 offset:17408
	ds_read_b128 v[176:179], v209 offset:18432
	ds_read_b128 v[180:183], v209 offset:19456
	ds_read_b128 v[212:215], v209 offset:20480
	ds_read_b128 v[216:219], v209 offset:21504
	ds_read_b128 v[220:223], v209 offset:22528
	ds_read_b128 v[224:227], v209 offset:23552
	global_load_lds_dwordx4 v[228:229], off
	s_add_i32 m0, s14, 0x2000
	s_add_u32 s14, s10, 0x40000
	v_lshl_add_u64 v[230:231], s[10:11], 0, v[192:193]
	s_addc_u32 s15, s11, 0
	s_add_i32 vcc_hi, vcc_hi, s44
	global_load_lds_dwordx4 v[230:231], off
	v_lshl_add_u64 v[106:107], s[14:15], 0, v[188:189]
	s_mov_b32 m0, vcc_hi
	v_lshl_add_u64 v[232:233], s[64:65], 0, v[186:187]
	global_load_lds_dwordx4 v[106:107], off
	v_lshl_add_u64 v[106:107], s[14:15], 0, v[192:193]
	s_add_i32 m0, vcc_hi, 0x2000
	v_lshl_add_u64 v[234:235], s[64:65], 0, v[190:191]
	global_load_lds_dwordx4 v[106:107], off
	s_mov_b32 m0, s52
	s_nop 0
	global_load_lds_dwordx4 v[232:233], off
	s_mov_b32 m0, s53
	s_nop 0
	global_load_lds_dwordx4 v[234:235], off
	s_waitcnt vmcnt(8)
	s_waitcnt lgkmcnt(0)
	s_cmp_lg_u64 s[18:19], 0
	s_cbranch_scc0 .Lmy_b1_0_1
	s_barrier
; #define PG8_STAGE(bufoff, gbase, voff) do { _Pragma("unroll") for (int _i = 0; _i < 2; ++_i) \
;         __builtin_amdgcn_global_load_lds((const unsigned*)((const char*)(gbase) + (voff)[_i]), (PG8_LAS unsigned*)(lds + (bufoff) + ldsw + _i * 8192), 16, 0, 0); } while (0)
; #define PG8_LDA(dst, b, h) do { _Pragma("unroll") for (int m = 0; m < 4; ++m) _Pragma("unroll") for (int k = 0; k < 2; ++k) dst[m][k] = *(const PG8_LAS bf16x8*)(lds + PG8_SA(b, h) + aoff + m * 2048 + k * 1024); } while (0)
; #define PG8_LDB(dst, b, h) do { _Pragma("unroll") for (int n = 0; n < 2; ++n) _Pragma("unroll") for (int k = 0; k < 2; ++k) dst[n][k] = *(const PG8_LAS bf16x8*)(lds + PG8_SB(b, h) + boff + n * 2048 + k * 1024); } while (0)
; #define PG8_MMA(ai, bj, At, Bt) do { __builtin_amdgcn_s_setprio(1); _Pragma("unroll") for (int m = 0; m < 4; ++m) _Pragma("unroll") for (int n = 0; n < 2; ++n) _Pragma("unroll") for (int k = 0; k < 2; ++k) \
;         acc[ai][bj][m][n] = mma16<Epi::F16>(Bt[n][k], At[m][k], acc[ai][bj][m][n]); __builtin_amdgcn_s_setprio(0); } while (0)
; #define PG8_WAIT_V(n) asm volatile("s_waitcnt vmcnt(" #n ")" ::: "memory")
; #define PG8_WAIT_L(n) asm volatile("s_waitcnt lgkmcnt(" #n ")" ::: "memory")
; #define PG8_BAR __builtin_amdgcn_s_barrier()
; #define PG8_SCHED __builtin_amdgcn_sched_barrier(0)
; template <class Epi, class Sched, bool ALIGN_EPI = false, bool SP2 = false>
; __device__ __forceinline__ void gemm_phase(PG8_LAS unsigned char* lds, const Gemm g, const Sched& S, const Epi& E) {
;     ...
;             PG8_WAIT_V(8); PG8_WAIT_L(0); PG8_BAR; PG8_MMA(1, 0, At, B0); PG8_MMA(1, 1, At, B1); PG8_BAR; PG8_SCHED;
;             PG8_LDB(B0, 1, 0); PG8_LDB(B1, 1, 1); PG8_SCHED; PG8_LDA(At, 1, 0); PG8_STAGE(PG8_SA(0, 1), a2 + hstep, voffA);
;             PG8_WAIT_V(8); PG8_WAIT_L(0); PG8_BAR; PG8_MMA(0, 0, At, B0); PG8_MMA(0, 1, At, B1); PG8_BAR; PG8_SCHED;
.Lmy_b1_0_1:
	s_waitcnt lgkmcnt(0)
	v_mfma_f32_16x16x32_f16 v[94:97], v[128:131], v[168:171], v[94:97]
	v_mfma_f32_16x16x32_f16 v[28:31], v[136:139], v[168:171], v[28:31]
	v_mfma_f32_16x16x32_f16 v[86:89], v[128:131], v[176:179], v[86:89]
	v_mfma_f32_16x16x32_f16 v[20:23], v[136:139], v[176:179], v[20:23]
	v_mfma_f32_16x16x32_f16 v[78:81], v[128:131], v[212:215], v[78:81]
	v_mfma_f32_16x16x32_f16 v[12:15], v[136:139], v[212:215], v[12:15]
	v_mfma_f32_16x16x32_f16 v[74:77], v[128:131], v[220:223], v[74:77]
	v_mfma_f32_16x16x32_f16 v[8:11], v[136:139], v[220:223], v[8:11]
	v_mfma_f32_16x16x32_f16 v[94:97], v[132:135], v[172:175], v[94:97]
	v_mfma_f32_16x16x32_f16 v[28:31], v[140:143], v[172:175], v[28:31]
	v_mfma_f32_16x16x32_f16 v[86:89], v[132:135], v[180:183], v[86:89]
	v_mfma_f32_16x16x32_f16 v[20:23], v[140:143], v[180:183], v[20:23]
	v_mfma_f32_16x16x32_f16 v[78:81], v[132:135], v[216:219], v[78:81]
	v_mfma_f32_16x16x32_f16 v[12:15], v[140:143], v[216:219], v[12:15]
	v_mfma_f32_16x16x32_f16 v[74:77], v[132:135], v[224:227], v[74:77]
	v_mfma_f32_16x16x32_f16 v[8:11], v[140:143], v[224:227], v[8:11]
	v_mfma_f32_16x16x32_f16 v[90:93], v[144:147], v[168:171], v[90:93]
	v_mfma_f32_16x16x32_f16 v[24:27], v[152:155], v[168:171], v[24:27]
	v_mfma_f32_16x16x32_f16 v[82:85], v[144:147], v[176:179], v[82:85]
	v_mfma_f32_16x16x32_f16 v[16:19], v[152:155], v[176:179], v[16:19]
	v_mfma_f32_16x16x32_f16 v[70:73], v[144:147], v[212:215], v[70:73]
	v_mfma_f32_16x16x32_f16 v[4:7], v[152:155], v[212:215], v[4:7]
	v_mfma_f32_16x16x32_f16 v[66:69], v[144:147], v[220:223], v[66:69]
	v_mfma_f32_16x16x32_f16 v[0:3], v[152:155], v[220:223], v[0:3]
	v_mfma_f32_16x16x32_f16 v[90:93], v[148:151], v[172:175], v[90:93]
	v_mfma_f32_16x16x32_f16 v[24:27], v[156:159], v[172:175], v[24:27]
	v_mfma_f32_16x16x32_f16 v[82:85], v[148:151], v[180:183], v[82:85]
	v_mfma_f32_16x16x32_f16 v[16:19], v[156:159], v[180:183], v[16:19]
	v_mfma_f32_16x16x32_f16 v[70:73], v[148:151], v[216:219], v[70:73]
	v_mfma_f32_16x16x32_f16 v[4:7], v[156:159], v[216:219], v[4:7]
	v_mfma_f32_16x16x32_f16 v[66:69], v[148:151], v[224:227], v[66:69]
	v_mfma_f32_16x16x32_f16 v[0:3], v[156:159], v[224:227], v[0:3]
	s_cmp_lg_u64 s[18:19], 0
	s_cbranch_scc1 .Lmy_b2_0_1
	s_barrier
.Lmy_b2_0_1:
	s_add_i32 vcc_hi, 0, 0x18000
	v_add_u32_e32 v106, vcc_hi, v185
	s_add_i32 s51, 0, 0x1c000
	ds_read_b128 v[128:131], v106
	ds_read_b128 v[132:135], v106 offset:1024
	ds_read_b128 v[136:139], v106 offset:2048
	ds_read_b128 v[140:143], v106 offset:3072
	v_add_u32_e32 v106, s51, v185
	ds_read_b128 v[144:147], v106
	ds_read_b128 v[148:151], v106 offset:1024
	ds_read_b128 v[152:155], v106 offset:2048
	ds_read_b128 v[156:159], v106 offset:3072
	s_add_u32 s14, s64, 0x40000
	s_addc_u32 s15, s65, 0
	s_mov_b32 m0, s59
	v_lshl_add_u64 v[106:107], s[14:15], 0, v[186:187]
	ds_read_b128 v[168:171], v209 offset:32768
	ds_read_b128 v[172:175], v209 offset:33792
	ds_read_b128 v[176:179], v209 offset:34816
	ds_read_b128 v[180:183], v209 offset:35840
	ds_read_b128 v[212:215], v209 offset:36864
	ds_read_b128 v[216:219], v209 offset:37888
	ds_read_b128 v[220:223], v209 offset:38912
	ds_read_b128 v[224:227], v209 offset:39936
	global_load_lds_dwordx4 v[106:107], off
	v_lshl_add_u64 v[106:107], s[14:15], 0, v[190:191]
	s_mov_b32 m0, s60
	s_nop 0
	global_load_lds_dwordx4 v[106:107], off
	s_waitcnt vmcnt(8)
	s_waitcnt lgkmcnt(0)
	s_cmp_lg_u64 s[18:19], 0
	s_cbranch_scc0 .Lmy_b1_0_2
	s_barrier
; #define PG8_STAGE(bufoff, gbase, voff) do { _Pragma("unroll") for (int _i = 0; _i < 2; ++_i) \
;         __builtin_amdgcn_global_load_lds((const unsigned*)((const char*)(gbase) + (voff)[_i]), (PG8_LAS unsigned*)(lds + (bufoff) + ldsw + _i * 8192), 16, 0, 0); } while (0)
; #define PG8_LDA(dst, b, h) do { _Pragma("unroll") for (int m = 0; m < 4; ++m) _Pragma("unroll") for (int k = 0; k < 2; ++k) dst[m][k] = *(const PG8_LAS bf16x8*)(lds + PG8_SA(b, h) + aoff + m * 2048 + k * 1024); } while (0)
; #define PG8_MMA(ai, bj, At, Bt) do { __builtin_amdgcn_s_setprio(1); _Pragma("unroll") for (int m = 0; m < 4; ++m) _Pragma("unroll") for (int n = 0; n < 2; ++n) _Pragma("unroll") for (int k = 0; k < 2; ++k) \
;         acc[ai][bj][m][n] = mma16<Epi::F16>(Bt[n][k], At[m][k], acc[ai][bj][m][n]); __builtin_amdgcn_s_setprio(0); } while (0)
; #define PG8_WAIT_V(n) asm volatile("s_waitcnt vmcnt(" #n ")" ::: "memory")
; #define PG8_WAIT_L(n) asm volatile("s_waitcnt lgkmcnt(" #n ")" ::: "memory")
; #define PG8_BAR __builtin_amdgcn_s_barrier()
; #define PG8_SCHED __builtin_amdgcn_sched_barrier(0)
; template <class Epi, class Sched, bool ALIGN_EPI = false, bool SP2 = false>
; __device__ __forceinline__ void gemm_phase(PG8_LAS unsigned char* lds, const Gemm g, const Sched& S, const Epi& E) {
;     ...
;             PG8_WAIT_V(8); PG8_WAIT_L(0); PG8_BAR; PG8_MMA(0, 0, At, B0); PG8_MMA(0, 1, At, B1); PG8_BAR; PG8_SCHED;
;             PG8_LDA(At, 1, 1); PG8_STAGE(PG8_SB(1, 0), b3, voffB); PG8_STAGE(PG8_SB(1, 1), b3 + hstep, voffB); PG8_STAGE(PG8_SA(1, 0), a3, voffA);
;             PG8_WAIT_V(8); PG8_WAIT_L(0); PG8_BAR; PG8_MMA(1, 0, At, B0); PG8_MMA(1, 1, At, B1); PG8_BAR; PG8_SCHED;
.Lmy_b1_0_2:
	s_waitcnt lgkmcnt(0)
	v_mfma_f32_16x16x32_f16 v[164:167], v[128:131], v[168:171], v[164:167]
	v_mfma_f32_16x16x32_f16 v[62:65], v[136:139], v[168:171], v[62:65]
	v_mfma_f32_16x16x32_f16 v[122:125], v[128:131], v[176:179], v[124:127]
	v_mfma_f32_16x16x32_f16 v[54:57], v[136:139], v[176:179], v[54:57]
	v_mfma_f32_16x16x32_f16 v[112:115], v[128:131], v[212:215], v[114:117]
	v_mfma_f32_16x16x32_f16 v[44:47], v[136:139], v[212:215], v[44:47]
	v_mfma_f32_16x16x32_f16 v[106:109], v[128:131], v[220:223], v[108:111]
	v_mfma_f32_16x16x32_f16 v[40:43], v[136:139], v[220:223], v[40:43]
	v_mfma_f32_16x16x32_f16 v[164:167], v[132:135], v[172:175], v[164:167]
	v_mfma_f32_16x16x32_f16 v[62:65], v[140:143], v[172:175], v[62:65]
	v_mfma_f32_16x16x32_f16 v[124:127], v[132:135], v[180:183], v[122:125]
	v_mfma_f32_16x16x32_f16 v[54:57], v[140:143], v[180:183], v[54:57]
	v_mfma_f32_16x16x32_f16 v[114:117], v[132:135], v[216:219], v[112:115]
	v_mfma_f32_16x16x32_f16 v[44:47], v[140:143], v[216:219], v[44:47]
	v_mfma_f32_16x16x32_f16 v[110:113], v[132:135], v[224:227], v[106:109]
	v_mfma_f32_16x16x32_f16 v[40:43], v[140:143], v[224:227], v[40:43]
	v_mfma_f32_16x16x32_f16 v[106:109], v[144:147], v[168:171], v[160:163]
	v_mfma_f32_16x16x32_f16 v[160:163], v[148:151], v[172:175], v[106:109]
	v_mfma_f32_16x16x32_f16 v[58:61], v[152:155], v[168:171], v[58:61]
	v_mfma_f32_16x16x32_f16 v[106:109], v[144:147], v[176:179], v[118:121]
	v_mfma_f32_16x16x32_f16 v[50:53], v[152:155], v[176:179], v[50:53]
	v_mfma_f32_16x16x32_f16 v[102:105], v[144:147], v[212:215], v[102:105]
	v_mfma_f32_16x16x32_f16 v[36:39], v[152:155], v[212:215], v[36:39]
	v_mfma_f32_16x16x32_f16 v[98:101], v[144:147], v[220:223], v[98:101]
	v_mfma_f32_16x16x32_f16 v[32:35], v[152:155], v[220:223], v[32:35]
	v_mfma_f32_16x16x32_f16 v[58:61], v[156:159], v[172:175], v[58:61]
	v_mfma_f32_16x16x32_f16 v[120:123], v[148:151], v[180:183], v[106:109]
	v_mfma_f32_16x16x32_f16 v[50:53], v[156:159], v[180:183], v[50:53]
	v_mfma_f32_16x16x32_f16 v[104:107], v[148:151], v[216:219], v[102:105]
	v_mfma_f32_16x16x32_f16 v[36:39], v[156:159], v[216:219], v[36:39]
	v_mfma_f32_16x16x32_f16 v[98:101], v[148:151], v[224:227], v[98:101]
	v_mfma_f32_16x16x32_f16 v[32:35], v[156:159], v[224:227], v[32:35]
	s_cmp_lg_u64 s[18:19], 0
	s_cbranch_scc1 .Lmy_b2_0_2
	s_barrier
.Lmy_b2_0_2:
	s_add_i32 s14, vcc_hi, s44
	v_lshl_add_u64 v[102:103], v[228:229], 0, s[88:89]
	s_mov_b32 m0, s14
	ds_read_b128 v[168:171], v209 offset:49152
	ds_read_b128 v[172:175], v209 offset:50176
	ds_read_b128 v[176:179], v209 offset:51200
	ds_read_b128 v[180:183], v209 offset:52224
	ds_read_b128 v[212:215], v209 offset:53248
	ds_read_b128 v[216:219], v209 offset:54272
	ds_read_b128 v[220:223], v209 offset:55296
	ds_read_b128 v[224:227], v209 offset:56320
	global_load_lds_dwordx4 v[102:103], off
	s_add_i32 m0, s14, 0x2000
	s_add_u32 s10, s10, 0x40080
	v_lshl_add_u64 v[102:103], v[230:231], 0, s[88:89]
	s_addc_u32 s11, s11, 0
	s_add_i32 s14, s51, s44
	global_load_lds_dwordx4 v[102:103], off
	v_lshl_add_u64 v[102:103], s[10:11], 0, v[188:189]
	s_mov_b32 m0, s14
	s_nop 0
	global_load_lds_dwordx4 v[102:103], off
	v_lshl_add_u64 v[102:103], s[10:11], 0, v[192:193]
	s_add_i32 m0, s14, 0x2000
	s_nop 0
	global_load_lds_dwordx4 v[102:103], off
	v_lshl_add_u64 v[102:103], v[232:233], 0, s[88:89]
	s_mov_b32 m0, s61
	s_nop 0
	global_load_lds_dwordx4 v[102:103], off
	v_lshl_add_u64 v[102:103], v[234:235], 0, s[88:89]
	s_mov_b32 m0, s63
	s_nop 0
	global_load_lds_dwordx4 v[102:103], off
	s_waitcnt vmcnt(8)
	s_waitcnt lgkmcnt(0)
	s_cmp_lg_u64 s[18:19], 0
	s_cbranch_scc0 .Lmy_b1_0_3
	s_barrier

; #define PG8_BAR __builtin_amdgcn_s_barrier()
; template <class Epi, class Sched, bool ALIGN_EPI = false, bool SP2 = false>
; __device__ __forceinline__ void gemm_phase(PG8_LAS unsigned char* lds, const Gemm g, const Sched& S, const Epi& E) {
;     ...
;         for (int t = 0; t < nt; t += 2) {
;             const bool last = (t == nt - 2);
;     ...
;         if constexpr (ALIGN_EPI) { if (wr == 0) PG8_BAR; }
.Lmy_b2_0_3:
	s_add_i32 vcc_lo, vcc_lo, 2
	s_add_u32 s8, s8, 0x100
	s_addc_u32 s9, s9, 0
	s_add_u32 s98, s98, 0x100
	s_addc_u32 s99, s99, 0
	s_cmp_gt_u32 vcc_lo, 13
	s_cbranch_scc0 .LBB0_92
	s_and_b64 vcc, exec, s[20:21]
	s_cbranch_vccz .LBB0_95

; #define PG8_LAS __attribute__((address_space(3)))
;     __device__ __forceinline__ void operator()(const f32x4 (&acc)[2][2][4][2], const Unit& u, int wr, int wc, int fr, int fq) const {
;     ...
; #pragma unroll
;             for (int ai = 0; ai < 2; ++ai) {
;                 const int k = 2 * ai + wr;
;                 const int rslot = k > 0 ? k - 1 : 0;
;                 PG8_LAS const unsigned char* hp = hl + rslot * 2048 + (lcol + 4 * n) * 4;
;                 f32x4 hg2 = *(PG8_LAS const f32x4*)hp, hv2 = *(PG8_LAS const f32x4*)(hp + 512), hg1 = *(PG8_LAS const f32x4*)(hp + 1024), hv1 = *(PG8_LAS const f32x4*)(hp + 1536);
;                 if (k == 0) { hg2 = (f32x4){0.f, 0.f, 0.f, 0.f}; hv2 = hg2; hg1 = hg2; hv1 = hg2; }
; #pragma unroll
;                 for (int m = 0; m < 4; ++m) {
;                     float r[4];
; #pragma unroll
;                     for (int e = 0; e < 4; ++e) {
;                         const float xg = acc[ai][0][m][n][e], xv = acc[ai][1][m][n][e];
;                         float o1g, o2g, o1v, o2v;
;                         if (m == 0) { o1g = hg1[e]; o2g = fr == 0 ? hg2[e] : hg1[e]; o1v = hv1[e]; o2v = fr == 0 ? hv2[e] : hv1[e]; }
;                         else { const float pgv = acc[ai][0][m > 0 ? m - 1 : 0][n][e], pvv = acc[ai][1][m > 0 ? m - 1 : 0][n][e];
;                             o1g = dpp_mov<0x121>(pgv, pgv); o2g = dpp_mov<0x122>(pgv, pgv); o1v = dpp_mov<0x121>(pvv, pvv); o2v = dpp_mov<0x122>(pvv, pvv); }
;                         const float p1g = dpp_mov<0x111>(o1g, xg), p2g = dpp_mov<0x112>(o2g, xg), p1v = dpp_mov<0x111>(o1v, xv), p2v = dpp_mov<0x112>(o2v, xv);
;                         const float yg = bg[e] + wg2[e] * xg + wg1[e] * p1g + wg0[e] * p2g;
;                         const float yv = bv[e] + wv2[e] * xv + wv1[e] * p1v + wv0[e] * p2v;
;                         r[e] = yg * __builtin_amdgcn_rcpf(1.0f + __builtin_amdgcn_exp2f(-1.4426950408889634f * yg)) * yv;
;                     }
;                     u32x2e w; w.x = cvt_pk_bf16(r[0], r[1]); w.y = cvt_pk_bf16(r[2], r[3]);
;                     if (n == 0) keep[ai][m] = w;
;                     else { const u32x4 w4 = (u32x4){keep[ai][m].x, keep[ai][m].y, w.x, w.y}; *(u32x4*)(O + (size_t)(u.pm * BM + ai * HALF + wr * 64 + m * 16 + fr) * ldo + f - 4) = w4; }
.LBB0_115:
	v_mov_b32_e32 v46, v24
	v_mov_b32_e32 v47, v28
	v_cndmask_b32_e64 v44, v40, v32, s[4:5]
	v_cndmask_b32_e64 v45, v41, v36, s[4:5]
	v_mov_b32_dpp v41, v28 row_shr:1 row_mask:0xf bank_mask:0xf
	v_mov_b32_dpp v40, v24 row_shr:1 row_mask:0xf bank_mask:0xf
	v_pk_fma_f32 v[46:47], v[46:47], v[96:97], v[128:129]
	v_mov_b32_dpp v45, v28 row_shr:2 row_mask:0xf bank_mask:0xf
	v_mov_b32_dpp v44, v24 row_shr:2 row_mask:0xf bank_mask:0xf
	v_pk_fma_f32 v[40:41], v[130:131], v[40:41], v[46:47]
	v_mov_b32_e32 v36, v25
	v_pk_fma_f32 v[40:41], v[124:125], v[44:45], v[40:41]
	v_add_u32_e32 v54, 0x80, v138
	v_mul_f32_e32 v32, 0xbfb8aa3b, v41
	v_exp_f32_e32 v32, v32
	s_andn2_b64 vcc, exec, s[6:7]
	v_add_f32_e32 v32, 1.0, v32
	v_rcp_f32_e32 v32, v32
	s_nop 0
	v_mul_f32_e32 v32, v41, v32
	v_mul_f32_e32 v40, v40, v32
	v_cndmask_b32_e64 v32, v52, v33, s[4:5]
	v_cndmask_b32_e64 v33, v53, v37, s[4:5]
	v_mov_b32_e32 v37, v29
	v_mov_b32_dpp v53, v29 row_shr:1 row_mask:0xf bank_mask:0xf
	v_mov_b32_dpp v52, v25 row_shr:1 row_mask:0xf bank_mask:0xf
	v_pk_fma_f32 v[36:37], v[36:37], v[76:77], v[80:81]
	v_mov_b32_dpp v33, v29 row_shr:2 row_mask:0xf bank_mask:0xf
	v_mov_b32_dpp v32, v25 row_shr:2 row_mask:0xf bank_mask:0xf
	v_pk_fma_f32 v[36:37], v[72:73], v[52:53], v[36:37]
	s_nop 0
	v_pk_fma_f32 v[32:33], v[68:69], v[32:33], v[36:37]
	v_mov_b32_e32 v37, v30
	v_mul_f32_e32 v36, 0xbfb8aa3b, v33
	v_exp_f32_e32 v36, v36
	s_nop 0
	v_add_f32_e32 v36, 1.0, v36
	v_rcp_f32_e32 v36, v36
	s_nop 0
	v_mul_f32_e32 v33, v33, v36
	v_mov_b32_e32 v36, v26
	v_mul_f32_e32 v41, v32, v33
	v_cndmask_b32_e64 v32, v42, v34, s[4:5]
	v_cndmask_b32_e64 v33, v43, v38, s[4:5]
	v_mov_b32_dpp v43, v30 row_shr:1 row_mask:0xf bank_mask:0xf
	v_mov_b32_dpp v42, v26 row_shr:1 row_mask:0xf bank_mask:0xf
	v_pk_fma_f32 v[36:37], v[36:37], v[114:115], v[132:133]
	v_mov_b32_dpp v33, v30 row_shr:2 row_mask:0xf bank_mask:0xf
	v_mov_b32_dpp v32, v26 row_shr:2 row_mask:0xf bank_mask:0xf
	v_pk_fma_f32 v[36:37], v[134:135], v[42:43], v[36:37]
	v_cvt_pk_bf16_f32 v100, v40, v41
	v_mov_b32_e32 v38, v16
	v_pk_fma_f32 v[32:33], v[126:127], v[32:33], v[36:37]
	s_nop 0
	v_mul_f32_e32 v34, 0xbfb8aa3b, v33
	v_exp_f32_e32 v34, v34
	s_nop 0
	v_add_f32_e32 v34, 1.0, v34
	v_rcp_f32_e32 v34, v34
	s_nop 0
	v_mul_f32_e32 v33, v33, v34
	v_mul_f32_e32 v36, v32, v33
	v_cndmask_b32_e64 v32, v50, v35, s[4:5]
	v_mov_b32_e32 v34, v27
	v_mov_b32_e32 v35, v31
	v_cndmask_b32_e64 v33, v51, v39, s[4:5]
	v_mov_b32_dpp v51, v31 row_shr:1 row_mask:0xf bank_mask:0xf
	v_mov_b32_dpp v50, v27 row_shr:1 row_mask:0xf bank_mask:0xf
	v_pk_fma_f32 v[34:35], v[34:35], v[78:79], v[82:83]
	v_mov_b32_dpp v33, v31 row_shr:2 row_mask:0xf bank_mask:0xf
	v_mov_b32_dpp v32, v27 row_shr:2 row_mask:0xf bank_mask:0xf
	v_pk_fma_f32 v[34:35], v[74:75], v[50:51], v[34:35]
	v_mov_b32_e32 v39, v20
	v_pk_fma_f32 v[32:33], v[70:71], v[32:33], v[34:35]
	v_pk_fma_f32 v[38:39], v[38:39], v[96:97], v[128:129]
	v_mul_f32_e32 v34, 0xbfb8aa3b, v33
	v_exp_f32_e32 v34, v34
	s_nop 0
	v_add_f32_e32 v34, 1.0, v34
	v_rcp_f32_e32 v34, v34
	s_nop 0
	v_mul_f32_e32 v33, v33, v34
	v_mul_f32_e32 v32, v32, v33
	v_cvt_pk_bf16_f32 v101, v36, v32
	v_mov_b64_e32 v[32:33], s[42:43]
	v_mad_i64_i32 v[34:35], s[8:9], v54, s80, v[32:33]
	v_lshl_add_u64 v[34:35], v[34:35], 0, v[88:89]
	global_store_dwordx4 v[34:35], v[98:101], off
	v_mov_b32_e32 v35, v28
	v_mov_b32_e32 v34, v24
	v_mov_b32_dpp v28, v28 row_ror:2 row_mask:0xf bank_mask:0xf
	v_mov_b32_dpp v35, v35 row_ror:1 row_mask:0xf bank_mask:0xf
	v_mov_b32_dpp v34, v34 row_ror:1 row_mask:0xf bank_mask:0xf
	v_mov_b32_dpp v24, v24 row_ror:2 row_mask:0xf bank_mask:0xf
	v_mov_b32_dpp v35, v20 row_shr:1 row_mask:0xf bank_mask:0xf
	v_mov_b32_dpp v28, v20 row_shr:2 row_mask:0xf bank_mask:0xf
	v_mov_b32_dpp v34, v16 row_shr:1 row_mask:0xf bank_mask:0xf
	v_mov_b32_dpp v24, v16 row_shr:2 row_mask:0xf bank_mask:0xf
	v_mov_b32_e32 v36, v24
	v_mov_b32_e32 v37, v28
	v_pk_fma_f32 v[34:35], v[130:131], v[34:35], v[38:39]
	s_nop 0
	v_pk_fma_f32 v[34:35], v[124:125], v[36:37], v[34:35]
	s_nop 0
	v_mul_f32_e32 v24, 0xbfb8aa3b, v35
	v_exp_f32_e32 v24, v24
	s_nop 0
	v_add_f32_e32 v24, 1.0, v24
	v_rcp_f32_e32 v24, v24
	s_nop 0
	v_mul_f32_e32 v24, v35, v24
	v_mul_f32_e32 v36, v34, v24
	v_mov_b32_e32 v34, v25
	v_mov_b32_dpp v25, v25 row_ror:2 row_mask:0xf bank_mask:0xf
	v_mov_b32_e32 v35, v29
	v_mov_b32_dpp v34, v34 row_ror:1 row_mask:0xf bank_mask:0xf
	v_mov_b32_dpp v25, v17 row_shr:2 row_mask:0xf bank_mask:0xf
	v_mov_b32_dpp v35, v35 row_ror:1 row_mask:0xf bank_mask:0xf
	v_mov_b32_e32 v28, v25
	v_mov_b32_e32 v24, v17
	v_mov_b32_e32 v25, v21
	v_mov_b32_dpp v29, v29 row_ror:2 row_mask:0xf bank_mask:0xf
	v_mov_b32_dpp v35, v21 row_shr:1 row_mask:0xf bank_mask:0xf
	v_mov_b32_dpp v34, v17 row_shr:1 row_mask:0xf bank_mask:0xf
	v_pk_fma_f32 v[24:25], v[24:25], v[76:77], v[80:81]
	v_mov_b32_dpp v29, v21 row_shr:2 row_mask:0xf bank_mask:0xf
	v_pk_fma_f32 v[24:25], v[72:73], v[34:35], v[24:25]
	v_mov_b32_e32 v34, v18
	v_pk_fma_f32 v[24:25], v[68:69], v[28:29], v[24:25]
	v_mov_b32_e32 v35, v22
	v_mul_f32_e32 v28, 0xbfb8aa3b, v25
	v_exp_f32_e32 v28, v28
	v_pk_fma_f32 v[34:35], v[34:35], v[114:115], v[132:133]
	v_add_f32_e32 v28, 1.0, v28
	v_rcp_f32_e32 v28, v28
	s_nop 0
	v_mul_f32_e32 v25, v25, v28
	v_mul_f32_e32 v37, v24, v25
	v_mov_b32_e32 v25, v30
	v_mov_b32_e32 v24, v26
	v_mov_b32_dpp v30, v30 row_ror:2 row_mask:0xf bank_mask:0xf
	v_mov_b32_dpp v25, v25 row_ror:1 row_mask:0xf bank_mask:0xf
	v_mov_b32_dpp v24, v24 row_ror:1 row_mask:0xf bank_mask:0xf
	v_mov_b32_dpp v26, v26 row_ror:2 row_mask:0xf bank_mask:0xf
	v_mov_b32_dpp v25, v22 row_shr:1 row_mask:0xf bank_mask:0xf
; __device__ __forceinline__ unsigned cvt_pk_bf16(float lo, float hi) { unsigned r; asm volatile("v_cvt_pk_bf16_f32 %0, %1, %2" : "=v"(r) : "v"(lo), "v"(hi)); return r; }
;     __device__ __forceinline__ void operator()(const f32x4 (&acc)[2][2][4][2], const Unit& u, int wr, int wc, int fr, int fq) const {
;     ...
;                 for (int m = 0; m < 4; ++m) {
;                     float r[4];
; #pragma unroll
;                     for (int e = 0; e < 4; ++e) {
;                         const float xg = acc[ai][0][m][n][e], xv = acc[ai][1][m][n][e];
;                         float o1g, o2g, o1v, o2v;
;                         if (m == 0) { o1g = hg1[e]; o2g = fr == 0 ? hg2[e] : hg1[e]; o1v = hv1[e]; o2v = fr == 0 ? hv2[e] : hv1[e]; }
;                         else { const float pgv = acc[ai][0][m > 0 ? m - 1 : 0][n][e], pvv = acc[ai][1][m > 0 ? m - 1 : 0][n][e];
;                             o1g = dpp_mov<0x121>(pgv, pgv); o2g = dpp_mov<0x122>(pgv, pgv); o1v = dpp_mov<0x121>(pvv, pvv); o2v = dpp_mov<0x122>(pvv, pvv); }
;                         const float p1g = dpp_mov<0x111>(o1g, xg), p2g = dpp_mov<0x112>(o2g, xg), p1v = dpp_mov<0x111>(o1v, xv), p2v = dpp_mov<0x112>(o2v, xv);
;                         const float yg = bg[e] + wg2[e] * xg + wg1[e] * p1g + wg0[e] * p2g;
;                         const float yv = bv[e] + wv2[e] * xv + wv1[e] * p1v + wv0[e] * p2v;
;                         r[e] = yg * __builtin_amdgcn_rcpf(1.0f + __builtin_amdgcn_exp2f(-1.4426950408889634f * yg)) * yv;
;                     }
;                     u32x2e w; w.x = cvt_pk_bf16(r[0], r[1]); w.y = cvt_pk_bf16(r[2], r[3]);
;                     if (n == 0) keep[ai][m] = w;
;                     else { const u32x4 w4 = (u32x4){keep[ai][m].x, keep[ai][m].y, w.x, w.y}; *(u32x4*)(O + (size_t)(u.pm * BM + ai * HALF + wr * 64 + m * 16 + fr) * ldo + f - 4) = w4; }
	v_mov_b32_dpp v30, v22 row_shr:2 row_mask:0xf bank_mask:0xf
	v_mov_b32_dpp v24, v18 row_shr:1 row_mask:0xf bank_mask:0xf
	v_mov_b32_dpp v26, v18 row_shr:2 row_mask:0xf bank_mask:0xf
	v_mov_b32_e32 v28, v26
	v_mov_b32_e32 v29, v30
	v_pk_fma_f32 v[24:25], v[134:135], v[24:25], v[34:35]
	v_cvt_pk_bf16_f32 v92, v36, v37
	s_nop 0
	v_pk_fma_f32 v[24:25], v[126:127], v[28:29], v[24:25]
	v_mov_b32_e32 v29, v12
	v_mul_f32_e32 v26, 0xbfb8aa3b, v25
	v_exp_f32_e32 v26, v26
	s_nop 0
	v_add_f32_e32 v26, 1.0, v26
	v_rcp_f32_e32 v26, v26
	s_nop 0
	v_mul_f32_e32 v25, v25, v26
	v_mul_f32_e32 v28, v24, v25
	v_mov_b32_e32 v24, v27
	v_mov_b32_dpp v27, v27 row_ror:2 row_mask:0xf bank_mask:0xf
	v_mov_b32_e32 v25, v31
	v_mov_b32_dpp v24, v24 row_ror:1 row_mask:0xf bank_mask:0xf
	v_mov_b32_dpp v27, v19 row_shr:2 row_mask:0xf bank_mask:0xf
	v_mov_b32_dpp v25, v25 row_ror:1 row_mask:0xf bank_mask:0xf
	v_mov_b32_e32 v30, v27
	v_mov_b32_e32 v26, v19
	v_mov_b32_e32 v27, v23
	v_mov_b32_dpp v31, v31 row_ror:2 row_mask:0xf bank_mask:0xf
	v_mov_b32_dpp v25, v23 row_shr:1 row_mask:0xf bank_mask:0xf
	v_mov_b32_dpp v24, v19 row_shr:1 row_mask:0xf bank_mask:0xf
	v_pk_fma_f32 v[26:27], v[26:27], v[78:79], v[82:83]
	v_mov_b32_dpp v31, v23 row_shr:2 row_mask:0xf bank_mask:0xf
	v_pk_fma_f32 v[24:25], v[74:75], v[24:25], v[26:27]
	s_nop 0
	v_pk_fma_f32 v[24:25], v[70:71], v[30:31], v[24:25]
	s_nop 0
	v_mul_f32_e32 v26, 0xbfb8aa3b, v25
	v_exp_f32_e32 v26, v26
	s_nop 0
	v_add_f32_e32 v26, 1.0, v26
	v_rcp_f32_e32 v26, v26
	s_nop 0
	v_mul_f32_e32 v25, v25, v26
	v_mul_f32_e32 v24, v24, v25
	v_cvt_pk_bf16_f32 v93, v28, v24
	v_add_u32_e32 v24, 0x90, v138
	v_mad_i64_i32 v[24:25], s[8:9], v24, s80, v[32:33]
	v_lshl_add_u64 v[24:25], v[24:25], 0, v[88:89]
	global_store_dwordx4 v[24:25], v[90:93], off
	v_mov_b32_e32 v25, v20
	v_mov_b32_e32 v24, v16
	v_mov_b32_dpp v20, v20 row_ror:2 row_mask:0xf bank_mask:0xf
	v_mov_b32_dpp v25, v25 row_ror:1 row_mask:0xf bank_mask:0xf
	v_mov_b32_dpp v24, v24 row_ror:1 row_mask:0xf bank_mask:0xf
	v_mov_b32_dpp v16, v16 row_ror:2 row_mask:0xf bank_mask:0xf
	v_mov_b32_e32 v28, v4
	v_mov_b32_dpp v25, v12 row_shr:1 row_mask:0xf bank_mask:0xf
	v_mov_b32_dpp v20, v12 row_shr:2 row_mask:0xf bank_mask:0xf
	v_mov_b32_dpp v24, v4 row_shr:1 row_mask:0xf bank_mask:0xf
	v_mov_b32_dpp v16, v4 row_shr:2 row_mask:0xf bank_mask:0xf
	v_pk_fma_f32 v[28:29], v[28:29], v[96:97], v[128:129]
	v_mov_b32_e32 v26, v16
	v_mov_b32_e32 v27, v20
	v_pk_fma_f32 v[24:25], v[130:131], v[24:25], v[28:29]
	s_nop 0
	v_pk_fma_f32 v[24:25], v[124:125], v[26:27], v[24:25]
	s_nop 0
	v_mul_f32_e32 v16, 0xbfb8aa3b, v25
	v_exp_f32_e32 v16, v16
	s_nop 0
	v_add_f32_e32 v16, 1.0, v16
	v_rcp_f32_e32 v16, v16
	s_nop 0
	v_mul_f32_e32 v16, v25, v16
	v_mul_f32_e32 v26, v24, v16
	v_mov_b32_e32 v24, v17
	v_mov_b32_dpp v17, v17 row_ror:2 row_mask:0xf bank_mask:0xf
	v_mov_b32_e32 v25, v21
	v_mov_b32_dpp v24, v24 row_ror:1 row_mask:0xf bank_mask:0xf
	v_mov_b32_dpp v17, v5 row_shr:2 row_mask:0xf bank_mask:0xf
	v_mov_b32_dpp v25, v25 row_ror:1 row_mask:0xf bank_mask:0xf
	v_mov_b32_e32 v20, v17
	v_mov_b32_e32 v16, v5
	v_mov_b32_e32 v17, v13
	v_mov_b32_dpp v21, v21 row_ror:2 row_mask:0xf bank_mask:0xf
	v_mov_b32_dpp v25, v13 row_shr:1 row_mask:0xf bank_mask:0xf
	v_mov_b32_dpp v24, v5 row_shr:1 row_mask:0xf bank_mask:0xf
	v_pk_fma_f32 v[16:17], v[16:17], v[76:77], v[80:81]
	v_mov_b32_dpp v21, v13 row_shr:2 row_mask:0xf bank_mask:0xf
	v_pk_fma_f32 v[16:17], v[72:73], v[24:25], v[16:17]
	v_mov_b32_e32 v24, v6
	v_pk_fma_f32 v[16:17], v[68:69], v[20:21], v[16:17]
	v_mov_b32_e32 v25, v14
	v_mul_f32_e32 v20, 0xbfb8aa3b, v17
	v_exp_f32_e32 v20, v20
	v_pk_fma_f32 v[24:25], v[24:25], v[114:115], v[132:133]
	v_add_f32_e32 v20, 1.0, v20
	v_rcp_f32_e32 v20, v20
	s_nop 0
	v_mul_f32_e32 v17, v17, v20
	v_mul_f32_e32 v27, v16, v17
	v_mov_b32_e32 v17, v22
	v_mov_b32_e32 v16, v18
	v_mov_b32_dpp v22, v22 row_ror:2 row_mask:0xf bank_mask:0xf
	v_mov_b32_dpp v17, v17 row_ror:1 row_mask:0xf bank_mask:0xf
	v_mov_b32_dpp v16, v16 row_ror:1 row_mask:0xf bank_mask:0xf
	v_mov_b32_dpp v18, v18 row_ror:2 row_mask:0xf bank_mask:0xf
	v_mov_b32_dpp v17, v14 row_shr:1 row_mask:0xf bank_mask:0xf
	v_mov_b32_dpp v22, v14 row_shr:2 row_mask:0xf bank_mask:0xf
	v_mov_b32_dpp v16, v6 row_shr:1 row_mask:0xf bank_mask:0xf
	v_mov_b32_dpp v18, v6 row_shr:2 row_mask:0xf bank_mask:0xf
	v_mov_b32_e32 v20, v18
	v_mov_b32_e32 v21, v22
	v_pk_fma_f32 v[16:17], v[134:135], v[16:17], v[24:25]
	v_cvt_pk_bf16_f32 v86, v26, v27
	s_nop 0
	v_pk_fma_f32 v[16:17], v[126:127], v[20:21], v[16:17]
	v_mov_b32_e32 v21, v8
	v_mul_f32_e32 v18, 0xbfb8aa3b, v17
	v_exp_f32_e32 v18, v18
	s_nop 0
	v_add_f32_e32 v18, 1.0, v18
	v_rcp_f32_e32 v18, v18
	s_nop 0
	v_mul_f32_e32 v17, v17, v18
	v_mul_f32_e32 v20, v16, v17
	v_mov_b32_e32 v16, v19
	v_mov_b32_dpp v19, v19 row_ror:2 row_mask:0xf bank_mask:0xf
	v_mov_b32_e32 v17, v23
	v_mov_b32_dpp v16, v16 row_ror:1 row_mask:0xf bank_mask:0xf
	v_mov_b32_dpp v19, v7 row_shr:2 row_mask:0xf bank_mask:0xf
; __device__ __forceinline__ unsigned cvt_pk_bf16(float lo, float hi) { unsigned r; asm volatile("v_cvt_pk_bf16_f32 %0, %1, %2" : "=v"(r) : "v"(lo), "v"(hi)); return r; }
; #define PG8_BAR __builtin_amdgcn_s_barrier()
;     __device__ __forceinline__ void operator()(const f32x4 (&acc)[2][2][4][2], const Unit& u, int wr, int wc, int fr, int fq) const {
;     ...
;                 for (int m = 0; m < 4; ++m) {
;                     float r[4];
; #pragma unroll
;                     for (int e = 0; e < 4; ++e) {
;                         const float xg = acc[ai][0][m][n][e], xv = acc[ai][1][m][n][e];
;                         float o1g, o2g, o1v, o2v;
;                         if (m == 0) { o1g = hg1[e]; o2g = fr == 0 ? hg2[e] : hg1[e]; o1v = hv1[e]; o2v = fr == 0 ? hv2[e] : hv1[e]; }
;                         else { const float pgv = acc[ai][0][m > 0 ? m - 1 : 0][n][e], pvv = acc[ai][1][m > 0 ? m - 1 : 0][n][e];
;                             o1g = dpp_mov<0x121>(pgv, pgv); o2g = dpp_mov<0x122>(pgv, pgv); o1v = dpp_mov<0x121>(pvv, pvv); o2v = dpp_mov<0x122>(pvv, pvv); }
;                         const float p1g = dpp_mov<0x111>(o1g, xg), p2g = dpp_mov<0x112>(o2g, xg), p1v = dpp_mov<0x111>(o1v, xv), p2v = dpp_mov<0x112>(o2v, xv);
;                         const float yg = bg[e] + wg2[e] * xg + wg1[e] * p1g + wg0[e] * p2g;
;                         const float yv = bv[e] + wv2[e] * xv + wv1[e] * p1v + wv0[e] * p2v;
;                         r[e] = yg * __builtin_amdgcn_rcpf(1.0f + __builtin_amdgcn_exp2f(-1.4426950408889634f * yg)) * yv;
;                     }
;                     u32x2e w; w.x = cvt_pk_bf16(r[0], r[1]); w.y = cvt_pk_bf16(r[2], r[3]);
;                     if (n == 0) keep[ai][m] = w;
;                     else { const u32x4 w4 = (u32x4){keep[ai][m].x, keep[ai][m].y, w.x, w.y}; *(u32x4*)(O + (size_t)(u.pm * BM + ai * HALF + wr * 64 + m * 16 + fr) * ldo + f - 4) = w4; }
; template <class Epi, class Sched, bool ALIGN_EPI = false, bool SP2 = false>
; __device__ __forceinline__ void gemm_phase(PG8_LAS unsigned char* lds, const Gemm g, const Sched& S, const Epi& E) {
;     ...
;         if constexpr (ALIGN_EPI) { if (wr == 1) PG8_BAR; }
	v_mov_b32_dpp v17, v17 row_ror:1 row_mask:0xf bank_mask:0xf
	v_mov_b32_e32 v22, v19
	v_mov_b32_e32 v18, v7
	v_mov_b32_e32 v19, v15
	v_mov_b32_dpp v23, v23 row_ror:2 row_mask:0xf bank_mask:0xf
	v_mov_b32_dpp v17, v15 row_shr:1 row_mask:0xf bank_mask:0xf
	v_mov_b32_dpp v16, v7 row_shr:1 row_mask:0xf bank_mask:0xf
	v_pk_fma_f32 v[18:19], v[18:19], v[78:79], v[82:83]
	v_mov_b32_dpp v23, v15 row_shr:2 row_mask:0xf bank_mask:0xf
	v_pk_fma_f32 v[16:17], v[74:75], v[16:17], v[18:19]
	s_nop 0
	v_pk_fma_f32 v[16:17], v[70:71], v[22:23], v[16:17]
	s_nop 0
	v_mul_f32_e32 v18, 0xbfb8aa3b, v17
	v_exp_f32_e32 v18, v18
	s_nop 0
	v_add_f32_e32 v18, 1.0, v18
	v_rcp_f32_e32 v18, v18
	s_nop 0
	v_mul_f32_e32 v17, v17, v18
	v_mul_f32_e32 v16, v16, v17
	v_cvt_pk_bf16_f32 v87, v20, v16
	v_add_u32_e32 v16, 0xa0, v138
	v_mad_i64_i32 v[16:17], s[8:9], v16, s80, v[32:33]
	v_lshl_add_u64 v[16:17], v[16:17], 0, v[88:89]
	global_store_dwordx4 v[16:17], v[84:87], off
	v_mov_b32_e32 v17, v12
	v_mov_b32_e32 v16, v4
	v_mov_b32_dpp v12, v12 row_ror:2 row_mask:0xf bank_mask:0xf
	v_mov_b32_dpp v17, v17 row_ror:1 row_mask:0xf bank_mask:0xf
	v_mov_b32_dpp v16, v16 row_ror:1 row_mask:0xf bank_mask:0xf
	v_mov_b32_dpp v4, v4 row_ror:2 row_mask:0xf bank_mask:0xf
	v_mov_b32_e32 v20, v0
	v_mov_b32_dpp v17, v8 row_shr:1 row_mask:0xf bank_mask:0xf
	v_mov_b32_dpp v12, v8 row_shr:2 row_mask:0xf bank_mask:0xf
	v_mov_b32_dpp v16, v0 row_shr:1 row_mask:0xf bank_mask:0xf
	v_mov_b32_dpp v4, v0 row_shr:2 row_mask:0xf bank_mask:0xf
	v_pk_fma_f32 v[20:21], v[20:21], v[96:97], v[128:129]
	v_mov_b32_e32 v18, v4
	v_mov_b32_e32 v19, v12
	v_pk_fma_f32 v[16:17], v[130:131], v[16:17], v[20:21]
	v_mov_b32_e32 v8, v1
	v_pk_fma_f32 v[16:17], v[124:125], v[18:19], v[16:17]
	s_nop 0
	v_mul_f32_e32 v0, 0xbfb8aa3b, v17
	v_exp_f32_e32 v0, v0
	s_nop 0
	v_add_f32_e32 v0, 1.0, v0
	v_rcp_f32_e32 v0, v0
	s_nop 0
	v_mul_f32_e32 v0, v17, v0
	v_mul_f32_e32 v18, v16, v0
	v_mov_b32_e32 v17, v13
	v_mov_b32_e32 v16, v5
	v_mov_b32_dpp v5, v5 row_ror:2 row_mask:0xf bank_mask:0xf
	v_mov_b32_dpp v17, v17 row_ror:1 row_mask:0xf bank_mask:0xf
	v_mov_b32_dpp v16, v16 row_ror:1 row_mask:0xf bank_mask:0xf
	v_mov_b32_dpp v13, v13 row_ror:2 row_mask:0xf bank_mask:0xf
	v_mov_b32_dpp v17, v9 row_shr:1 row_mask:0xf bank_mask:0xf
	v_mov_b32_dpp v16, v1 row_shr:1 row_mask:0xf bank_mask:0xf
	v_mov_b32_dpp v5, v1 row_shr:2 row_mask:0xf bank_mask:0xf
	v_pk_fma_f32 v[0:1], v[8:9], v[76:77], v[80:81]
	v_mov_b32_dpp v13, v9 row_shr:2 row_mask:0xf bank_mask:0xf
	v_mov_b32_e32 v12, v5
	v_pk_fma_f32 v[0:1], v[72:73], v[16:17], v[0:1]
	v_mov_b32_e32 v8, v2
	v_pk_fma_f32 v[0:1], v[68:69], v[12:13], v[0:1]
	v_mov_b32_e32 v9, v10
	v_mul_f32_e32 v4, 0xbfb8aa3b, v1
	v_exp_f32_e32 v4, v4
	v_pk_fma_f32 v[8:9], v[8:9], v[114:115], v[132:133]
	v_add_f32_e32 v4, 1.0, v4
	v_rcp_f32_e32 v4, v4
	s_nop 0
	v_mul_f32_e32 v1, v1, v4
	v_mul_f32_e32 v12, v0, v1
	v_mov_b32_e32 v1, v14
	v_mov_b32_e32 v0, v6
	v_mov_b32_dpp v14, v14 row_ror:2 row_mask:0xf bank_mask:0xf
	v_mov_b32_dpp v1, v1 row_ror:1 row_mask:0xf bank_mask:0xf
	v_mov_b32_dpp v0, v0 row_ror:1 row_mask:0xf bank_mask:0xf
	v_mov_b32_dpp v6, v6 row_ror:2 row_mask:0xf bank_mask:0xf
	v_mov_b32_dpp v1, v10 row_shr:1 row_mask:0xf bank_mask:0xf
	v_mov_b32_dpp v14, v10 row_shr:2 row_mask:0xf bank_mask:0xf
	v_mov_b32_dpp v0, v2 row_shr:1 row_mask:0xf bank_mask:0xf
	v_mov_b32_dpp v6, v2 row_shr:2 row_mask:0xf bank_mask:0xf
	v_mov_b32_e32 v4, v6
	v_mov_b32_e32 v5, v14
	v_pk_fma_f32 v[0:1], v[134:135], v[0:1], v[8:9]
	v_mov_b32_e32 v10, v3
	v_pk_fma_f32 v[0:1], v[126:127], v[4:5], v[0:1]
	v_cvt_pk_bf16_f32 v68, v18, v12
	s_nop 0
	v_mul_f32_e32 v2, 0xbfb8aa3b, v1
	v_exp_f32_e32 v2, v2
	s_nop 0
	v_add_f32_e32 v2, 1.0, v2
	v_rcp_f32_e32 v2, v2
	s_nop 0
	v_mul_f32_e32 v1, v1, v2
	v_mul_f32_e32 v4, v0, v1
	v_mov_b32_e32 v1, v15
	v_mov_b32_e32 v0, v7
	v_mov_b32_dpp v7, v7 row_ror:2 row_mask:0xf bank_mask:0xf
	v_mov_b32_dpp v1, v1 row_ror:1 row_mask:0xf bank_mask:0xf
	v_mov_b32_dpp v0, v0 row_ror:1 row_mask:0xf bank_mask:0xf
	v_mov_b32_dpp v15, v15 row_ror:2 row_mask:0xf bank_mask:0xf
	v_mov_b32_dpp v1, v11 row_shr:1 row_mask:0xf bank_mask:0xf
	v_mov_b32_dpp v0, v3 row_shr:1 row_mask:0xf bank_mask:0xf
	v_mov_b32_dpp v7, v3 row_shr:2 row_mask:0xf bank_mask:0xf
	v_pk_fma_f32 v[2:3], v[10:11], v[78:79], v[82:83]
	v_mov_b32_dpp v15, v11 row_shr:2 row_mask:0xf bank_mask:0xf
	v_mov_b32_e32 v14, v7
	v_pk_fma_f32 v[0:1], v[74:75], v[0:1], v[2:3]
	s_nop 0
	v_pk_fma_f32 v[0:1], v[70:71], v[14:15], v[0:1]
	s_nop 0
	v_mul_f32_e32 v2, 0xbfb8aa3b, v1
	v_exp_f32_e32 v2, v2
	s_nop 0
	v_add_f32_e32 v2, 1.0, v2
	v_rcp_f32_e32 v2, v2
	s_nop 0
	v_mul_f32_e32 v1, v1, v2
	v_mul_f32_e32 v0, v0, v1
	v_cvt_pk_bf16_f32 v69, v4, v0
	v_add_u32_e32 v0, 0xb0, v138
	v_mad_i64_i32 v[0:1], s[8:9], v0, s80, v[32:33]
	v_lshl_add_u64 v[0:1], v[0:1], 0, v[88:89]
	s_mov_b64 s[8:9], -1
	global_store_dwordx4 v[0:1], v[66:69], off
	s_cbranch_vccnz .LBB0_86
	s_andn2_b64 vcc, exec, s[18:19]
	s_cbranch_vccnz .LBB0_85
	s_branch .LBB0_85

; #define PG8_WAIT_V(n) asm volatile("s_waitcnt vmcnt(" #n ")" ::: "memory")
; #define PG8_BAR __builtin_amdgcn_s_barrier()
; template <class Epi, class Sched, bool ALIGN_EPI = false, bool SP2 = false>
; __device__ __forceinline__ void gemm_phase(PG8_LAS unsigned char* lds, const Gemm g, const Sched& S, const Epi& E) {
;     ...
;     PG8_WAIT_V(0);
;     if constexpr (!ALIGN_EPI) { if (wr == 0) PG8_BAR; }
;     PG8_BAR;
.LBB0_121:
	s_waitcnt vmcnt(0)
	v_readlane_b32 s20, v242, 7
	s_mov_b32 s51, s73
	v_readlane_b32 s76, v242, 10
	s_mov_b64 s[24:25], s[0:1]
	v_readlane_b32 s91, v242, 9
	v_readlane_b32 s21, v242, 8
	s_barrier
	s_setprio 0

; __device__ __forceinline__ int opaque_tid() { int t = threadIdx.x; asm volatile("" : "+v"(t)); return t; }
; #define PG8_WAIT_V(n) asm volatile("s_waitcnt vmcnt(" #n ")" ::: "memory")
; template <class Epi, class Sched, bool ALIGN_EPI = false, bool SP2 = false>
; __device__ __forceinline__ void gemm_phase(PG8_LAS unsigned char* lds, const Gemm g, const Sched& S, const Epi& E) {
;     const int tid = opaque_tid(), wid = __builtin_amdgcn_readfirstlane(tid >> 6), lane = tid & 63, wr = wid >> 2, wc = wid & 3, fr = lane & 15, fq = lane >> 4;
;     const int K = g.K, nt = K / BK;
;     unsigned voffA[2], voffB[2];
; #pragma unroll
;     for (int i = 0; i < 2; ++i) { int R, C; stage_rc(tid * 16 + i * 8192, R, C); const int Rb = Epi::PERM ? ((R & ~31) + perm32(R & 31)) : R;
;         voffA[i] = (unsigned)(R * K + C) * 2u; voffB[i] = (unsigned)(Rb * K + C) * 2u; }
;     const size_t kstep = (size_t)(BK * 2);
;     const size_t hstep = (size_t)HALF * K * 2;
;     const size_t tstep = 2 * hstep;
;     const unsigned ldsw = (unsigned)wid * 1024u;
;     const int aoff = lds_byte(wr * 64 + fr, fq * 8), boff = lds_byte(wc * 32 + fr, fq * 8);
;     ...
;     Unit cur, nxt; int ui = 0;
;     if (!S.next(0, cur)) return;
;     f32x4 acc[2][2][4][2];
; #pragma unroll
;     for (int a = 0; a < 2; ++a)
; #pragma unroll
;         for (int b = 0; b < 2; ++b)
; #pragma unroll
;             for (int m = 0; m < 4; ++m)
; #pragma unroll
;                 for (int n = 0; n < 2; ++n) acc[a][b][m][n] = (f32x4){0.f, 0.f, 0.f, 0.f};
;     bf16x8 At[4][2], B0[2][2], B1[2][2];
;     const char* cA = (const char*)g.A + (size_t)cur.pm * tstep; const char* cB = (const char*)g.Bt + (size_t)cur.pn * tstep;
;     S.a_ready(cur);
;     if constexpr (SP2) {
;         PG8_STAGE(PG8_SB(0, 0), cB, voffB); PG8_STAGE(PG8_SB(0, 1), cB + hstep, voffB); PG8_STAGE(PG8_SA(0, 0), cA, voffA); PG8_STAGE(PG8_SA(0, 1), cA + hstep, voffA);
;         if (wr == 1) PG8_BAR;
;         PG8_WAIT_V(2); PG8_BAR;
;         PG8_STAGE(PG8_SB(1, 0), cB + kstep, voffB); PG8_STAGE(PG8_SA(1, 0), cA + kstep, voffA); PG8_STAGE(PG8_SB(1, 1), cB + hstep + kstep, voffB);
;         PG8_WAIT_V(6); PG8_BAR;
;     } else {
;         PG8_STAGE(PG8_SB(0, 0), cB, voffB); PG8_STAGE(PG8_SA(0, 0), cA, voffA); PG8_STAGE(PG8_SB(0, 1), cB + hstep, voffB); PG8_STAGE(PG8_SA(0, 1), cA + hstep, voffA);
;         if (wr == 1) PG8_BAR;
.LBB0_141:
	s_and_b64 vcc, exec, s[4:5]
	s_cbranch_vccnz .LBB0_266
	v_ashrrev_i32_e32 v1, 31, v8
	v_lshrrev_b32_e32 v1, 26, v1
	v_add_u32_e32 v1, v8, v1
	v_ashrrev_i32_e32 v9, 6, v1
	v_bfe_i32 v1, v8, 27, 1
	v_lshlrev_b32_e32 v0, 4, v8
	v_lshrrev_b32_e32 v1, 22, v1
	v_add_u32_e32 v1, v0, v1
	v_and_b32_e32 v1, 0xfffffc00, v1
	v_sub_u32_e32 v1, v0, v1
	v_lshrrev_b32_e32 v2, 4, v1
	v_bitop3_b32 v2, v2, v1, 32 bitop3:0x6c
	v_ashrrev_i32_e32 v1, 31, v1
	v_lshrrev_b32_e32 v1, 26, v1
	v_add_u32_e32 v1, v2, v1
	v_ashrrev_i32_e32 v10, 6, v1
	v_lshlrev_b32_e32 v3, 3, v9
	v_mul_i32_i24_e32 v4, 64, v10
	v_and_b32_e32 v3, -16, v3
	v_sub_u32_e32 v2, v2, v4
	v_add_u32_e32 v1, v10, v3
	v_lshlrev_b32_e32 v3, 5, v9
	v_ashrrev_i16_sdwa v2, v205, sext(v2) dst_sel:DWORD dst_unused:UNUSED_PAD src0_sel:DWORD src1_sel:BYTE_0
	v_and_b32_e32 v3, 32, v3
	v_bfe_i32 v11, v2, 0, 16
	v_and_b32_e32 v5, 3, v10
	s_mov_b32 s5, 0x1fffe0
	v_add_lshl_u32 v3, v3, v11, 1
	v_add_u32_e32 v0, 0x2000, v0
	v_lshlrev_b32_e32 v2, 1, v1
	v_lshrrev_b32_e32 v4, 2, v1
	v_and_or_b32 v5, v1, s5, v5
	v_lshl_add_u32 v130, v1, 11, v3
	v_ashrrev_i32_e32 v1, 31, v0
	v_lshrrev_b32_e32 v1, 22, v1
	v_add_u32_e32 v1, v0, v1
	v_ashrrev_i32_e32 v12, 10, v1
	v_mul_i32_i24_e32 v1, 0x400, v12
	v_sub_u32_e32 v0, v0, v1
	v_and_b32_e32 v2, 24, v2
	v_and_b32_e32 v4, 4, v4
	v_lshrrev_b32_e32 v1, 4, v0
	v_or3_b32 v2, v5, v4, v2
	v_bitop3_b32 v0, v1, v0, 32 bitop3:0x6c
	v_lshl_add_u32 v132, v2, 11, v3
	v_ashrrev_i32_e32 v2, 31, v0
	v_lshrrev_b32_e32 v2, 26, v2
	v_lshlrev_b32_e32 v1, 3, v12
	v_add_u32_e32 v2, v0, v2
	v_and_b32_e32 v1, -16, v1
	v_ashrrev_i32_e32 v13, 6, v2
	s_ashr_i32 s4, s6, 6
	v_add_u32_e32 v1, v13, v1
	v_and_b32_e32 v2, 0xc0, v2
	v_and_b32_e32 v4, 3, v13
	s_ashr_i32 s19, s18, 31
	s_ashr_i32 s17, s16, 31
	v_sub_u32_e32 v0, v0, v2
	v_and_or_b32 v4, v1, s5, v4
	s_ashr_i32 s5, s6, 8
	s_lshl_b32 s38, s4, 10
	s_lshl_b64 s[8:9], s[18:19], 19
	s_lshl_b64 s[10:11], s[16:17], 19
	v_ashrrev_i16_sdwa v0, v205, sext(v0) dst_sel:DWORD dst_unused:UNUSED_PAD src0_sel:DWORD src1_sel:BYTE_0
	s_add_u32 s10, s49, s10
	v_lshlrev_b32_e32 v3, 5, v12
	v_bfe_i32 v14, v0, 0, 16
	v_lshlrev_b32_e32 v0, 1, v1
	v_lshrrev_b32_e32 v2, 2, v1
	s_addc_u32 s11, s70, s11
	s_add_i32 s17, s38, 0
	v_and_b32_e32 v3, 32, v3
	v_and_b32_e32 v0, 24, v0
	v_and_b32_e32 v2, 4, v2
	s_add_i32 m0, s17, 0x10000
	v_writelane_b32 v242, s20, 7
	v_or3_b32 v0, v4, v2, v0
	v_add_lshl_u32 v2, v3, v14, 1
	global_load_lds_dwordx4 v132, s[10:11]
	s_add_i32 m0, s17, 0x12000
	v_writelane_b32 v242, s21, 8
	v_lshl_add_u32 v136, v0, 11, v2
	s_add_u32 s20, s10, 0x40000
	global_load_lds_dwordx4 v136, s[10:11]
	s_addc_u32 s21, s11, 0
	s_add_i32 m0, s17, 0x14000
	v_lshl_add_u32 v134, v1, 11, v2
	global_load_lds_dwordx4 v132, s[20:21]
	s_add_i32 m0, s17, 0x16000
	s_add_u32 s8, s40, s8
	s_addc_u32 s9, s41, s9
	s_add_i32 s39, s17, 0x2000
	global_load_lds_dwordx4 v136, s[20:21]
	s_mov_b32 m0, s17
	s_add_u32 s20, s8, 0x40000
	global_load_lds_dwordx4 v130, s[8:9]
	s_mov_b32 m0, s39
	s_addc_u32 s21, s9, 0
	s_add_i32 s58, s17, 0x4000
	global_load_lds_dwordx4 v134, s[8:9]
	s_mov_b32 m0, s58
	s_add_i32 s59, s17, 0x6000
	global_load_lds_dwordx4 v130, s[20:21]
	s_mov_b32 m0, s59
	v_mov_b32_e32 v133, v48
	global_load_lds_dwordx4 v134, s[20:21]
	v_mov_b32_e32 v137, v48
	v_mov_b32_e32 v131, v48
	v_mov_b32_e32 v135, v48
	s_cmp_eq_u32 s5, 1
	v_lshl_add_u64 v[6:7], s[10:11], 0, v[132:133]
	v_lshl_add_u64 v[4:5], s[10:11], 0, v[136:137]
	v_lshl_add_u64 v[0:1], s[8:9], 0, v[130:131]
	s_cselect_b64 s[20:21], -1, 0
	s_cmp_lg_u32 s5, 1
	v_lshl_add_u64 v[2:3], s[8:9], 0, v[134:135]
	s_setprio 1
	s_cbranch_scc1 .LBB0_144
	s_setprio 2

; #define PG8_STAGE(bufoff, gbase, voff) do { _Pragma("unroll") for (int _i = 0; _i < 2; ++_i) \
;         __builtin_amdgcn_global_load_lds((const unsigned*)((const char*)(gbase) + (voff)[_i]), (PG8_LAS unsigned*)(lds + (bufoff) + ldsw + _i * 8192), 16, 0, 0); } while (0)
; #define PG8_LDA(dst, b, h) do { _Pragma("unroll") for (int m = 0; m < 4; ++m) _Pragma("unroll") for (int k = 0; k < 2; ++k) dst[m][k] = *(const PG8_LAS bf16x8*)(lds + PG8_SA(b, h) + aoff + m * 2048 + k * 1024); } while (0)
; #define PG8_LDB(dst, b, h) do { _Pragma("unroll") for (int n = 0; n < 2; ++n) _Pragma("unroll") for (int k = 0; k < 2; ++k) dst[n][k] = *(const PG8_LAS bf16x8*)(lds + PG8_SB(b, h) + boff + n * 2048 + k * 1024); } while (0)
; #define PG8_MMA(ai, bj, At, Bt) do { __builtin_amdgcn_s_setprio(1); _Pragma("unroll") for (int m = 0; m < 4; ++m) _Pragma("unroll") for (int n = 0; n < 2; ++n) _Pragma("unroll") for (int k = 0; k < 2; ++k) \
;         acc[ai][bj][m][n] = mma16<Epi::F16>(Bt[n][k], At[m][k], acc[ai][bj][m][n]); __builtin_amdgcn_s_setprio(0); } while (0)
; #define PG8_WAIT_V(n) asm volatile("s_waitcnt vmcnt(" #n ")" ::: "memory")
; #define PG8_WAIT_L(n) asm volatile("s_waitcnt lgkmcnt(" #n ")" ::: "memory")
; #define PG8_BAR __builtin_amdgcn_s_barrier()
; #define PG8_SCHED __builtin_amdgcn_sched_barrier(0)
; template <class Epi, class Sched, bool ALIGN_EPI = false, bool SP2 = false>
; __device__ __forceinline__ void gemm_phase(PG8_LAS unsigned char* lds, const Gemm g, const Sched& S, const Epi& E) {
;     ...
;             const bool last = (t == nt - 2);
;             const char* a1 = cA + (size_t)(t + 1) * kstep;
;             const char* a2 = last ? nA : cA + (size_t)(t + 2) * kstep; const char* b2 = last ? nB : cB + (size_t)(t + 2) * kstep;
;             const char* a3 = a2 + kstep; const char* b3 = b2 + kstep;
;             if (last && has_next) S.a_ready(nxt);
;             if constexpr (SP2) {
;             PG8_LDB(B0, 0, 0); PG8_LDB(B1, 0, 1); PG8_SCHED; PG8_LDA(At, 0, 0); PG8_STAGE(PG8_SA(1, 1), a1 + hstep, voffA);
;             PG8_WAIT_V(8); PG8_WAIT_L(0); PG8_BAR; PG8_MMA(0, 0, At, B0); PG8_MMA(0, 1, At, B1); PG8_BAR; PG8_SCHED;
.LBB0_152:
	s_add_u32 s10, s8, 0xfffc0080
	s_addc_u32 s11, s9, -1
	s_add_i32 s14, 0, 0x10000
	s_cmp_eq_u32 s52, 12
	s_cselect_b32 s35, s19, s11
	s_cselect_b32 s34, s27, s10
	v_add_u32_e32 v49, s14, v153
	s_cselect_b32 s11, s25, s44
	s_cselect_b32 s10, s36, s37
	s_add_i32 s15, 0, 0x14000
	ds_read_b128 v[142:145], v49
	ds_read_b128 v[146:149], v49 offset:1024
	ds_read_b128 v[158:161], v49 offset:2048
	ds_read_b128 v[162:165], v49 offset:3072
	v_add_u32_e32 v49, s15, v153
	ds_read_b128 v[166:169], v49
	ds_read_b128 v[170:173], v49 offset:1024
	ds_read_b128 v[174:177], v49 offset:2048
	ds_read_b128 v[178:181], v49 offset:3072
	v_lshl_add_u64 v[150:151], s[8:9], 0, v[138:139]
	s_add_i32 m0, s17, 0xc000
	ds_read_b128 v[186:189], v156
	ds_read_b128 v[190:193], v156 offset:1024
	ds_read_b128 v[194:197], v156 offset:2048
	ds_read_b128 v[198:201], v156 offset:3072
	ds_read_b128 v[208:211], v156 offset:4096
	ds_read_b128 v[212:215], v156 offset:5120
	ds_read_b128 v[216:219], v156 offset:6144
	ds_read_b128 v[220:223], v156 offset:7168
	global_load_lds_dwordx4 v[150:151], off
	v_lshl_add_u64 v[150:151], s[8:9], 0, v[140:141]
	s_add_i32 m0, s17, 0xe000
	s_nop 0
	global_load_lds_dwordx4 v[150:151], off
	s_waitcnt vmcnt(8)
	s_waitcnt lgkmcnt(0)
	s_cmp_lg_u64 s[20:21], 0
	s_cbranch_scc0 .Lmy_b1_1_0
	s_barrier
.Lmy_b1_1_0:
	s_waitcnt lgkmcnt(0)
	v_mfma_f32_16x16x32_f16 v[126:129], v[142:145], v[186:189], v[126:129]
	v_mfma_f32_16x16x32_f16 v[122:125], v[158:161], v[186:189], v[122:125]
	v_mfma_f32_16x16x32_f16 v[110:113], v[142:145], v[194:197], v[110:113]
	v_mfma_f32_16x16x32_f16 v[106:109], v[158:161], v[194:197], v[106:109]
	v_mfma_f32_16x16x32_f16 v[94:97], v[142:145], v[208:211], v[94:97]
	v_mfma_f32_16x16x32_f16 v[90:93], v[158:161], v[208:211], v[90:93]
	v_mfma_f32_16x16x32_f16 v[78:81], v[142:145], v[216:219], v[78:81]
	v_mfma_f32_16x16x32_f16 v[74:77], v[158:161], v[216:219], v[74:77]
	v_mfma_f32_16x16x32_f16 v[126:129], v[146:149], v[190:193], v[126:129]
	v_mfma_f32_16x16x32_f16 v[122:125], v[162:165], v[190:193], v[122:125]
	v_mfma_f32_16x16x32_f16 v[110:113], v[146:149], v[198:201], v[110:113]
	v_mfma_f32_16x16x32_f16 v[106:109], v[162:165], v[198:201], v[106:109]
	v_mfma_f32_16x16x32_f16 v[94:97], v[146:149], v[212:215], v[94:97]
	v_mfma_f32_16x16x32_f16 v[90:93], v[162:165], v[212:215], v[90:93]
	v_mfma_f32_16x16x32_f16 v[78:81], v[146:149], v[220:223], v[78:81]
	v_mfma_f32_16x16x32_f16 v[74:77], v[162:165], v[220:223], v[74:77]
	v_mfma_f32_16x16x32_f16 v[118:121], v[166:169], v[186:189], v[118:121]
	v_mfma_f32_16x16x32_f16 v[114:117], v[174:177], v[186:189], v[114:117]
	v_mfma_f32_16x16x32_f16 v[102:105], v[166:169], v[194:197], v[102:105]
	v_mfma_f32_16x16x32_f16 v[98:101], v[174:177], v[194:197], v[98:101]
	v_mfma_f32_16x16x32_f16 v[86:89], v[166:169], v[208:211], v[86:89]
	v_mfma_f32_16x16x32_f16 v[82:85], v[174:177], v[208:211], v[82:85]
	v_mfma_f32_16x16x32_f16 v[70:73], v[166:169], v[216:219], v[70:73]
	v_mfma_f32_16x16x32_f16 v[66:69], v[174:177], v[216:219], v[66:69]
	v_mfma_f32_16x16x32_f16 v[118:121], v[170:173], v[190:193], v[118:121]
	v_mfma_f32_16x16x32_f16 v[114:117], v[178:181], v[190:193], v[114:117]
	v_mfma_f32_16x16x32_f16 v[102:105], v[170:173], v[198:201], v[102:105]
	v_mfma_f32_16x16x32_f16 v[98:101], v[178:181], v[198:201], v[98:101]
	v_mfma_f32_16x16x32_f16 v[86:89], v[170:173], v[212:215], v[86:89]
	v_mfma_f32_16x16x32_f16 v[82:85], v[178:181], v[212:215], v[82:85]
	v_mfma_f32_16x16x32_f16 v[70:73], v[170:173], v[220:223], v[70:73]
	v_mfma_f32_16x16x32_f16 v[66:69], v[178:181], v[220:223], v[66:69]
	s_cmp_lg_u64 s[20:21], 0
	s_cbranch_scc1 .Lmy_b2_1_0
	s_barrier
; #define PG8_STAGE(bufoff, gbase, voff) do { _Pragma("unroll") for (int _i = 0; _i < 2; ++_i) \
;         __builtin_amdgcn_global_load_lds((const unsigned*)((const char*)(gbase) + (voff)[_i]), (PG8_LAS unsigned*)(lds + (bufoff) + ldsw + _i * 8192), 16, 0, 0); } while (0)
; #define PG8_LDA(dst, b, h) do { _Pragma("unroll") for (int m = 0; m < 4; ++m) _Pragma("unroll") for (int k = 0; k < 2; ++k) dst[m][k] = *(const PG8_LAS bf16x8*)(lds + PG8_SA(b, h) + aoff + m * 2048 + k * 1024); } while (0)
; #define PG8_LDB(dst, b, h) do { _Pragma("unroll") for (int n = 0; n < 2; ++n) _Pragma("unroll") for (int k = 0; k < 2; ++k) dst[n][k] = *(const PG8_LAS bf16x8*)(lds + PG8_SB(b, h) + boff + n * 2048 + k * 1024); } while (0)
; #define PG8_MMA(ai, bj, At, Bt) do { __builtin_amdgcn_s_setprio(1); _Pragma("unroll") for (int m = 0; m < 4; ++m) _Pragma("unroll") for (int n = 0; n < 2; ++n) _Pragma("unroll") for (int k = 0; k < 2; ++k) \
;         acc[ai][bj][m][n] = mma16<Epi::F16>(Bt[n][k], At[m][k], acc[ai][bj][m][n]); __builtin_amdgcn_s_setprio(0); } while (0)
; #define PG8_WAIT_V(n) asm volatile("s_waitcnt vmcnt(" #n ")" ::: "memory")
; #define PG8_WAIT_L(n) asm volatile("s_waitcnt lgkmcnt(" #n ")" ::: "memory")
; #define PG8_BAR __builtin_amdgcn_s_barrier()
; #define PG8_SCHED __builtin_amdgcn_sched_barrier(0)
; template <class Epi, class Sched, bool ALIGN_EPI = false, bool SP2 = false>
; __device__ __forceinline__ void gemm_phase(PG8_LAS unsigned char* lds, const Gemm g, const Sched& S, const Epi& E) {
;     ...
;             PG8_LDA(At, 0, 1); PG8_STAGE(PG8_SB(0, 0), b2, voffB); PG8_STAGE(PG8_SB(0, 1), b2 + hstep, voffB); PG8_STAGE(PG8_SA(0, 0), a2, voffA);
;             PG8_WAIT_V(8); PG8_WAIT_L(0); PG8_BAR; PG8_MMA(1, 0, At, B0); PG8_MMA(1, 1, At, B1); PG8_BAR; PG8_SCHED;
;             PG8_LDB(B0, 1, 0); PG8_LDB(B1, 1, 1); PG8_SCHED; PG8_LDA(At, 1, 0); PG8_STAGE(PG8_SA(0, 1), a2 + hstep, voffA);
;             PG8_WAIT_V(8); PG8_WAIT_L(0); PG8_BAR; PG8_MMA(0, 0, At, B0); PG8_MMA(0, 1, At, B1); PG8_BAR; PG8_SCHED;
.Lmy_b2_1_0:
	s_add_i32 s14, s14, s38
	v_lshl_add_u64 v[150:151], s[10:11], 0, v[132:133]
	s_mov_b32 m0, s14
	ds_read_b128 v[186:189], v156 offset:16384
	ds_read_b128 v[190:193], v156 offset:17408
	ds_read_b128 v[194:197], v156 offset:18432
	ds_read_b128 v[198:201], v156 offset:19456
	ds_read_b128 v[208:211], v156 offset:20480
	ds_read_b128 v[212:215], v156 offset:21504
	ds_read_b128 v[216:219], v156 offset:22528
	ds_read_b128 v[220:223], v156 offset:23552
	global_load_lds_dwordx4 v[150:151], off
	s_add_i32 m0, s14, 0x2000
	s_add_u32 s60, s10, 0x40000
	v_lshl_add_u64 v[182:183], s[10:11], 0, v[136:137]
	s_addc_u32 s61, s11, 0
	s_add_i32 s14, s15, s38
	global_load_lds_dwordx4 v[182:183], off
	v_lshl_add_u64 v[224:225], s[60:61], 0, v[132:133]
	s_mov_b32 m0, s14
	v_lshl_add_u64 v[226:227], s[34:35], 0, v[134:135]
	global_load_lds_dwordx4 v[224:225], off
	v_lshl_add_u64 v[224:225], s[60:61], 0, v[136:137]
	s_add_i32 m0, s14, 0x2000
	s_nop 0
	global_load_lds_dwordx4 v[224:225], off
	v_lshl_add_u64 v[224:225], s[34:35], 0, v[130:131]
	s_mov_b32 m0, s17
	s_nop 0
	global_load_lds_dwordx4 v[224:225], off
	s_mov_b32 m0, s39
	s_nop 0
	global_load_lds_dwordx4 v[226:227], off
	s_waitcnt vmcnt(8)
	s_waitcnt lgkmcnt(0)
	s_cmp_lg_u64 s[20:21], 0
	s_cbranch_scc0 .Lmy_b1_1_1
	s_barrier
.Lmy_b1_1_1:
	s_waitcnt lgkmcnt(0)
	v_mfma_f32_16x16x32_f16 v[62:65], v[142:145], v[186:189], v[62:65]
	v_mfma_f32_16x16x32_f16 v[58:61], v[158:161], v[186:189], v[58:61]
	v_mfma_f32_16x16x32_f16 v[44:47], v[142:145], v[194:197], v[44:47]
	v_mfma_f32_16x16x32_f16 v[40:43], v[158:161], v[194:197], v[40:43]
	v_mfma_f32_16x16x32_f16 v[28:31], v[142:145], v[208:211], v[28:31]
	v_mfma_f32_16x16x32_f16 v[24:27], v[158:161], v[208:211], v[24:27]
	v_mfma_f32_16x16x32_f16 v[12:15], v[142:145], v[216:219], v[12:15]
	v_mfma_f32_16x16x32_f16 v[8:11], v[158:161], v[216:219], v[8:11]
	v_mfma_f32_16x16x32_f16 v[62:65], v[146:149], v[190:193], v[62:65]
	v_mfma_f32_16x16x32_f16 v[58:61], v[162:165], v[190:193], v[58:61]
	v_mfma_f32_16x16x32_f16 v[44:47], v[146:149], v[198:201], v[44:47]
	v_mfma_f32_16x16x32_f16 v[40:43], v[162:165], v[198:201], v[40:43]
	v_mfma_f32_16x16x32_f16 v[28:31], v[146:149], v[212:215], v[28:31]
	v_mfma_f32_16x16x32_f16 v[24:27], v[162:165], v[212:215], v[24:27]
	v_mfma_f32_16x16x32_f16 v[12:15], v[146:149], v[220:223], v[12:15]
	v_mfma_f32_16x16x32_f16 v[8:11], v[162:165], v[220:223], v[8:11]
	v_mfma_f32_16x16x32_f16 v[54:57], v[166:169], v[186:189], v[54:57]
	v_mfma_f32_16x16x32_f16 v[50:53], v[174:177], v[186:189], v[50:53]
	v_mfma_f32_16x16x32_f16 v[36:39], v[166:169], v[194:197], v[36:39]
	v_mfma_f32_16x16x32_f16 v[32:35], v[174:177], v[194:197], v[32:35]
	v_mfma_f32_16x16x32_f16 v[20:23], v[166:169], v[208:211], v[20:23]
	v_mfma_f32_16x16x32_f16 v[16:19], v[174:177], v[208:211], v[16:19]
	v_mfma_f32_16x16x32_f16 v[4:7], v[166:169], v[216:219], v[4:7]
	v_mfma_f32_16x16x32_f16 v[0:3], v[174:177], v[216:219], v[0:3]
	v_mfma_f32_16x16x32_f16 v[54:57], v[170:173], v[190:193], v[54:57]
	v_mfma_f32_16x16x32_f16 v[50:53], v[178:181], v[190:193], v[50:53]
	v_mfma_f32_16x16x32_f16 v[36:39], v[170:173], v[198:201], v[36:39]
	v_mfma_f32_16x16x32_f16 v[32:35], v[178:181], v[198:201], v[32:35]
	v_mfma_f32_16x16x32_f16 v[20:23], v[170:173], v[212:215], v[20:23]
	v_mfma_f32_16x16x32_f16 v[16:19], v[178:181], v[212:215], v[16:19]
	v_mfma_f32_16x16x32_f16 v[4:7], v[170:173], v[220:223], v[4:7]
	v_mfma_f32_16x16x32_f16 v[0:3], v[178:181], v[220:223], v[0:3]
	s_cmp_lg_u64 s[20:21], 0
	s_cbranch_scc1 .Lmy_b2_1_1
	s_barrier
.Lmy_b2_1_1:
	s_add_i32 s14, 0, 0x18000
	v_add_u32_e32 v49, s14, v153
	s_add_i32 s15, 0, 0x1c000
	ds_read_b128 v[142:145], v49
	ds_read_b128 v[146:149], v49 offset:1024
	ds_read_b128 v[158:161], v49 offset:2048
	ds_read_b128 v[162:165], v49 offset:3072
	v_add_u32_e32 v49, s15, v153
	ds_read_b128 v[166:169], v49
	ds_read_b128 v[170:173], v49 offset:1024
	ds_read_b128 v[174:177], v49 offset:2048
	ds_read_b128 v[178:181], v49 offset:3072
	s_add_u32 s34, s34, 0x40000
	s_addc_u32 s35, s35, 0
	s_mov_b32 m0, s58
	v_lshl_add_u64 v[228:229], s[34:35], 0, v[130:131]
	ds_read_b128 v[186:189], v156 offset:32768
	ds_read_b128 v[190:193], v156 offset:33792
	ds_read_b128 v[194:197], v156 offset:34816
	ds_read_b128 v[198:201], v156 offset:35840
	ds_read_b128 v[208:211], v156 offset:36864
	ds_read_b128 v[212:215], v156 offset:37888
	ds_read_b128 v[216:219], v156 offset:38912
	ds_read_b128 v[220:223], v156 offset:39936
	global_load_lds_dwordx4 v[228:229], off
	v_lshl_add_u64 v[228:229], s[34:35], 0, v[134:135]
	s_mov_b32 m0, s59
	s_nop 0
	global_load_lds_dwordx4 v[228:229], off
	s_waitcnt vmcnt(8)
	s_waitcnt lgkmcnt(0)
	s_cmp_lg_u64 s[20:21], 0
	s_cbranch_scc0 .Lmy_b1_1_2
	s_barrier

; #define PG8_STAGE(bufoff, gbase, voff) do { _Pragma("unroll") for (int _i = 0; _i < 2; ++_i) \
;         __builtin_amdgcn_global_load_lds((const unsigned*)((const char*)(gbase) + (voff)[_i]), (PG8_LAS unsigned*)(lds + (bufoff) + ldsw + _i * 8192), 16, 0, 0); } while (0)
; #define PG8_LDA(dst, b, h) do { _Pragma("unroll") for (int m = 0; m < 4; ++m) _Pragma("unroll") for (int k = 0; k < 2; ++k) dst[m][k] = *(const PG8_LAS bf16x8*)(lds + PG8_SA(b, h) + aoff + m * 2048 + k * 1024); } while (0)
; #define PG8_MMA(ai, bj, At, Bt) do { __builtin_amdgcn_s_setprio(1); _Pragma("unroll") for (int m = 0; m < 4; ++m) _Pragma("unroll") for (int n = 0; n < 2; ++n) _Pragma("unroll") for (int k = 0; k < 2; ++k) \
;         acc[ai][bj][m][n] = mma16<Epi::F16>(Bt[n][k], At[m][k], acc[ai][bj][m][n]); __builtin_amdgcn_s_setprio(0); } while (0)
; #define PG8_WAIT_V(n) asm volatile("s_waitcnt vmcnt(" #n ")" ::: "memory")
; #define PG8_WAIT_L(n) asm volatile("s_waitcnt lgkmcnt(" #n ")" ::: "memory")
; #define PG8_BAR __builtin_amdgcn_s_barrier()
; #define PG8_SCHED __builtin_amdgcn_sched_barrier(0)
; template <class Epi, class Sched, bool ALIGN_EPI = false, bool SP2 = false>
; __device__ __forceinline__ void gemm_phase(PG8_LAS unsigned char* lds, const Gemm g, const Sched& S, const Epi& E) {
;     ...
;             PG8_LDA(At, 1, 1); PG8_STAGE(PG8_SB(1, 0), b3, voffB); PG8_STAGE(PG8_SB(1, 1), b3 + hstep, voffB); PG8_STAGE(PG8_SA(1, 0), a3, voffA);
;             PG8_WAIT_V(8); PG8_WAIT_L(0); PG8_BAR; PG8_MMA(1, 0, At, B0); PG8_MMA(1, 1, At, B1); PG8_BAR; PG8_SCHED;
.Lmy_b2_1_2:
	s_add_i32 s14, s14, s38
	v_lshl_add_u64 v[150:151], v[150:151], 0, s[88:89]
	s_mov_b32 m0, s14
	ds_read_b128 v[186:189], v156 offset:49152
	ds_read_b128 v[190:193], v156 offset:50176
	ds_read_b128 v[194:197], v156 offset:51200
	ds_read_b128 v[198:201], v156 offset:52224
	ds_read_b128 v[208:211], v156 offset:53248
	ds_read_b128 v[212:215], v156 offset:54272
	ds_read_b128 v[216:219], v156 offset:55296
	ds_read_b128 v[220:223], v156 offset:56320
	global_load_lds_dwordx4 v[150:151], off
	s_add_i32 m0, s14, 0x2000
	s_add_u32 s10, s10, 0x40080
	v_lshl_add_u64 v[150:151], v[182:183], 0, s[88:89]
	s_addc_u32 s11, s11, 0
	s_add_i32 s14, s15, s38
	global_load_lds_dwordx4 v[150:151], off
	v_lshl_add_u64 v[150:151], s[10:11], 0, v[132:133]
	s_mov_b32 m0, s14
	s_nop 0
	global_load_lds_dwordx4 v[150:151], off
	v_lshl_add_u64 v[150:151], s[10:11], 0, v[136:137]
	s_add_i32 m0, s14, 0x2000
	s_nop 0
	global_load_lds_dwordx4 v[150:151], off
	v_lshl_add_u64 v[150:151], v[224:225], 0, s[88:89]
	s_mov_b32 m0, s62
	s_nop 0
	global_load_lds_dwordx4 v[150:151], off
	v_lshl_add_u64 v[150:151], v[226:227], 0, s[88:89]
	s_mov_b32 m0, s63
	s_nop 0
	global_load_lds_dwordx4 v[150:151], off
	s_waitcnt vmcnt(8)
	s_waitcnt lgkmcnt(0)
	s_cmp_lg_u64 s[20:21], 0
	s_cbranch_scc0 .Lmy_b1_1_3
	s_barrier

; #define PG8_WAIT_V(n) asm volatile("s_waitcnt vmcnt(" #n ")" ::: "memory")
; template <class Epi, class Sched, bool ALIGN_EPI = false, bool SP2 = false>
; __device__ __forceinline__ void gemm_phase(PG8_LAS unsigned char* lds, const Gemm g, const Sched& S, const Epi& E) {
;     ...
;         for (int t = 0; t < nt; t += 2) {
;             const bool last = (t == nt - 2);
;             const char* a1 = cA + (size_t)(t + 1) * kstep;
;             const char* a2 = last ? nA : cA + (size_t)(t + 2) * kstep; const char* b2 = last ? nB : cB + (size_t)(t + 2) * kstep;
;             const char* a3 = a2 + kstep; const char* b3 = b2 + kstep;
;             if (last && has_next) S.a_ready(nxt);
;             if constexpr (SP2) {
;             PG8_LDB(B0, 0, 0); PG8_LDB(B1, 0, 1); PG8_SCHED; PG8_LDA(At, 0, 0); PG8_STAGE(PG8_SA(1, 1), a1 + hstep, voffA);
;             PG8_WAIT_V(8); PG8_WAIT_L(0); PG8_BAR; PG8_MMA(0, 0, At, B0); PG8_MMA(0, 1, At, B1); PG8_BAR; PG8_SCHED;
;             PG8_LDA(At, 0, 1); PG8_STAGE(PG8_SB(0, 0), b2, voffB); PG8_STAGE(PG8_SB(0, 1), b2 + hstep, voffB); PG8_STAGE(PG8_SA(0, 0), a2, voffA);
;             PG8_WAIT_V(8); PG8_WAIT_L(0); PG8_BAR; PG8_MMA(1, 0, At, B0); PG8_MMA(1, 1, At, B1); PG8_BAR; PG8_SCHED;
;             PG8_LDB(B0, 1, 0); PG8_LDB(B1, 1, 1); PG8_SCHED; PG8_LDA(At, 1, 0); PG8_STAGE(PG8_SA(0, 1), a2 + hstep, voffA);
;             PG8_WAIT_V(8); PG8_WAIT_L(0); PG8_BAR; PG8_MMA(0, 0, At, B0); PG8_MMA(0, 1, At, B1); PG8_BAR; PG8_SCHED;
;             PG8_LDA(At, 1, 1); PG8_STAGE(PG8_SB(1, 0), b3, voffB); PG8_STAGE(PG8_SB(1, 1), b3 + hstep, voffB); PG8_STAGE(PG8_SA(1, 0), a3, voffA);
;             PG8_WAIT_V(8); PG8_WAIT_L(0); PG8_BAR; PG8_MMA(1, 0, At, B0); PG8_MMA(1, 1, At, B1); PG8_BAR; PG8_SCHED;
;             } else {
;             PG8_LDB(B0, 0, 0); PG8_SCHED; PG8_LDA(At, 0, 0); PG8_STAGE(PG8_SA(1, 1), a1 + hstep, voffA);
;             PG8_WAIT_L(8); PG8_BAR; PG8_WAIT_L(0); PG8_MMA(0, 0, At, B0); PG8_BAR; PG8_SCHED;
;             PG8_LDB(B1, 0, 1); PG8_STAGE(PG8_SB(0, 0), b2, voffB);
;             PG8_BAR; PG8_WAIT_L(0); PG8_MMA(0, 1, At, B1); PG8_BAR;
;             PG8_LDA(At, 0, 1); PG8_STAGE(PG8_SA(0, 0), a2, voffA);
;             PG8_BAR; PG8_WAIT_L(0); PG8_MMA(1, 0, At, B0); PG8_BAR; PG8_SCHED;
;             PG8_STAGE(PG8_SB(0, 1), b2 + hstep, voffB);
;             PG8_WAIT_V(6); PG8_BAR; PG8_MMA(1, 1, At, B1); PG8_BAR;
.Lmy_b2_1_3:
	s_add_i32 s52, s52, 2
	s_add_u32 s8, s8, 0x100
	s_addc_u32 s9, s9, 0
	s_add_u32 s37, s37, 0x100
	s_addc_u32 s44, s44, 0
	s_cmp_gt_u32 s52, 13
	s_cbranch_scc0 .LBB0_152
	s_and_b64 vcc, exec, s[22:23]
	s_cbranch_vccz .LBB0_155

; #define PG8_BAR __builtin_amdgcn_s_barrier()
; template <class Epi, class Sched, bool ALIGN_EPI = false, bool SP2 = false>
; __device__ __forceinline__ void gemm_phase(PG8_LAS unsigned char* lds, const Gemm g, const Sched& S, const Epi& E) {
;     ...
;         if (!has_next) break;
; #pragma unroll
;         for (int a = 0; a < 2; ++a)
; #pragma unroll
;             for (int b = 0; b < 2; ++b)
; #pragma unroll
;                 for (int m = 0; m < 4; ++m)
; #pragma unroll
;                     for (int n = 0; n < 2; ++n) acc[a][b][m][n] = (f32x4){0.f, 0.f, 0.f, 0.f};
;         cur = nxt; cA = nA; cB = nB; ++ui;
;         if constexpr (ALIGN_EPI) { if (wr == 1) PG8_BAR; }
.LBB0_263:
	s_andn2_b64 vcc, exec, s[6:7]
	s_mov_b64 s[6:7], -1
	s_cbranch_vccnz .LBB0_146
	s_andn2_b64 vcc, exec, s[20:21]
	s_cbranch_vccnz .LBB0_145
	s_branch .LBB0_145

; #define PG8_WAIT_V(n) asm volatile("s_waitcnt vmcnt(" #n ")" ::: "memory")
; #define PG8_BAR __builtin_amdgcn_s_barrier()
; template <class Epi, class Sched, bool ALIGN_EPI = false, bool SP2 = false>
; __device__ __forceinline__ void gemm_phase(PG8_LAS unsigned char* lds, const Gemm g, const Sched& S, const Epi& E) {
;     ...
;     PG8_WAIT_V(0);
;     if constexpr (!ALIGN_EPI) { if (wr == 0) PG8_BAR; }
;     PG8_BAR;
.LBB0_267:
	s_waitcnt vmcnt(0)
	v_readlane_b32 s20, v242, 7
	s_barrier
	s_setprio 0
	s_mov_b32 s10, s76
	s_mov_b64 s[24:25], s[0:1]
	v_readlane_b32 s21, v242, 8

; __device__ __forceinline__ int opaque_tid() { int t = threadIdx.x; asm volatile("" : "+v"(t)); return t; }
; #define PG8_WAIT_V(n) asm volatile("s_waitcnt vmcnt(" #n ")" ::: "memory")
; template <class Epi, class Sched, bool ALIGN_EPI = false, bool SP2 = false>
; __device__ __forceinline__ void gemm_phase(PG8_LAS unsigned char* lds, const Gemm g, const Sched& S, const Epi& E) {
;     const int tid = opaque_tid(), wid = __builtin_amdgcn_readfirstlane(tid >> 6), lane = tid & 63, wr = wid >> 2, wc = wid & 3, fr = lane & 15, fq = lane >> 4;
;     const int K = g.K, nt = K / BK;
;     unsigned voffA[2], voffB[2];
; #pragma unroll
;     for (int i = 0; i < 2; ++i) { int R, C; stage_rc(tid * 16 + i * 8192, R, C); const int Rb = Epi::PERM ? ((R & ~31) + perm32(R & 31)) : R;
;         voffA[i] = (unsigned)(R * K + C) * 2u; voffB[i] = (unsigned)(Rb * K + C) * 2u; }
;     const size_t kstep = (size_t)(BK * 2);
;     const size_t hstep = (size_t)HALF * K * 2;
;     const size_t tstep = 2 * hstep;
;     const unsigned ldsw = (unsigned)wid * 1024u;
;     const int aoff = lds_byte(wr * 64 + fr, fq * 8), boff = lds_byte(wc * 32 + fr, fq * 8);
;     ...
;     Unit cur, nxt; int ui = 0;
;     if (!S.next(0, cur)) return;
;     f32x4 acc[2][2][4][2];
; #pragma unroll
;     for (int a = 0; a < 2; ++a)
; #pragma unroll
;         for (int b = 0; b < 2; ++b)
; #pragma unroll
;             for (int m = 0; m < 4; ++m)
; #pragma unroll
;                 for (int n = 0; n < 2; ++n) acc[a][b][m][n] = (f32x4){0.f, 0.f, 0.f, 0.f};
;     bf16x8 At[4][2], B0[2][2], B1[2][2];
;     const char* cA = (const char*)g.A + (size_t)cur.pm * tstep; const char* cB = (const char*)g.Bt + (size_t)cur.pn * tstep;
;     S.a_ready(cur);
;     if constexpr (SP2) {
;         PG8_STAGE(PG8_SB(0, 0), cB, voffB); PG8_STAGE(PG8_SB(0, 1), cB + hstep, voffB); PG8_STAGE(PG8_SA(0, 0), cA, voffA); PG8_STAGE(PG8_SA(0, 1), cA + hstep, voffA);
;         if (wr == 1) PG8_BAR;
;         PG8_WAIT_V(2); PG8_BAR;
;         PG8_STAGE(PG8_SB(1, 0), cB + kstep, voffB); PG8_STAGE(PG8_SA(1, 0), cA + kstep, voffA); PG8_STAGE(PG8_SB(1, 1), cB + hstep + kstep, voffB);
;         PG8_WAIT_V(6); PG8_BAR;
;     } else {
;         PG8_STAGE(PG8_SB(0, 0), cB, voffB); PG8_STAGE(PG8_SA(0, 0), cA, voffA); PG8_STAGE(PG8_SB(0, 1), cB + hstep, voffB); PG8_STAGE(PG8_SA(0, 1), cA + hstep, voffA);
;         if (wr == 1) PG8_BAR;
.LBB0_328:
	v_readlane_b32 s12, v243, 35
	s_or_b32 s17, s91, s12
	s_cmp_lg_u32 s17, 7
	s_cselect_b64 s[12:13], -1, 0
	s_and_b64 vcc, exec, s[4:5]
	s_cbranch_vccnz .LBB0_509
	v_bfe_i32 v2, v12, 27, 1
	v_lshlrev_b32_e32 v0, 4, v12
	v_lshrrev_b32_e32 v2, 22, v2
	v_add_u32_e32 v2, v0, v2
	v_and_b32_e32 v2, 0xfffffc00, v2
	v_readlane_b32 s4, v243, 44
	v_ashrrev_i32_e32 v1, 31, v12
	v_sub_u32_e32 v2, v0, v2
	s_or_b32 s4, s91, s4
	v_lshrrev_b32_e32 v1, 26, v1
	v_lshrrev_b32_e32 v3, 4, v2
	s_cmp_eq_u32 s4, 0
	v_add_u32_e32 v1, v12, v1
	v_bitop3_b32 v3, v3, v2, 32 bitop3:0x6c
	v_ashrrev_i32_e32 v2, 31, v2
	s_cselect_b64 s[4:5], -1, 0
	v_ashrrev_i32_e32 v1, 6, v1
	v_lshrrev_b32_e32 v2, 26, v2
	s_and_b64 s[22:23], s[4:5], exec
	v_readlane_b32 s19, v243, 41
	v_lshlrev_b32_e32 v4, 3, v1
	v_add_u32_e32 v2, v3, v2
	s_cselect_b32 s36, s19, s15
	v_readlane_b32 s15, v243, 40
	s_cselect_b32 s6, 0x27000000, s6
	v_and_b32_e32 v4, -16, v4
	v_ashrrev_i32_e32 v2, 6, v2
	v_lshlrev_b32_e32 v1, 5, v1
	s_cselect_b32 s37, s15, s14
	s_cselect_b32 s7, 0, s7
	s_add_u32 s38, s68, s6
	v_add_u32_e32 v4, v2, v4
	v_and_b32_e32 v13, 32, v1
	v_mul_i32_i24_e32 v1, 64, v2
	s_addc_u32 s39, s69, s7
	v_sub_u32_e32 v1, v3, v1
	v_lshlrev_b32_e32 v3, 1, v4
	v_lshrrev_b32_e32 v5, 2, v4
	v_and_b32_e32 v2, 3, v2
	s_mov_b32 s6, 0x7fffffe0
	s_and_b64 s[4:5], s[4:5], exec
	v_ashrrev_i16_sdwa v1, v205, sext(v1) dst_sel:DWORD dst_unused:UNUSED_PAD src0_sel:DWORD src1_sel:BYTE_0
	v_and_b32_e32 v3, 24, v3
	v_and_b32_e32 v5, 4, v5
	v_and_or_b32 v2, v4, s6, v2
	s_cselect_b32 s4, 0x400, s18
	v_bfe_i32 v14, v1, 0, 16
	v_or3_b32 v2, v2, v5, v3
	v_add_u32_e32 v1, v13, v14
	v_mul_lo_u32 v15, v4, s4
	v_mul_lo_u32 v2, v2, s4
	v_add_u32_e32 v0, 0x2000, v0
	v_add_lshl_u32 v138, v1, v15, 1
	v_add_lshl_u32 v140, v2, v1, 1
	v_ashrrev_i32_e32 v1, 31, v0
	v_lshrrev_b32_e32 v1, 22, v1
	v_add_u32_e32 v1, v0, v1
	v_ashrrev_i32_e32 v1, 10, v1
	v_mul_i32_i24_e32 v2, 0x400, v1
	v_sub_u32_e32 v0, v0, v2
	v_lshrrev_b32_e32 v2, 4, v0
	v_bitop3_b32 v0, v2, v0, 32 bitop3:0x6c
	v_ashrrev_i32_e32 v3, 31, v0
	v_lshrrev_b32_e32 v3, 26, v3
	v_lshlrev_b32_e32 v2, 3, v1
	v_add_u32_e32 v3, v0, v3
	v_writelane_b32 v242, s76, 10
	v_and_b32_e32 v2, -16, v2
	v_ashrrev_i32_e32 v4, 6, v3
	v_writelane_b32 v242, s51, 7
	s_ashr_i32 s5, s16, 6
	v_add_u32_e32 v2, v4, v2
	v_lshlrev_b32_e32 v1, 5, v1
	v_and_b32_e32 v4, 3, v4
	s_lshl_b32 s51, s4, 9
	v_and_b32_e32 v16, 32, v1
	v_and_b32_e32 v1, 0xc0, v3
	v_and_or_b32 v4, v2, s6, v4
	s_ashr_i32 s6, s16, 8
	s_lshl_b32 s44, s4, 8
	s_lshl_b32 s58, s5, 10
	s_mul_i32 s15, s51, s34
	v_sub_u32_e32 v0, v0, v1
	v_lshlrev_b32_e32 v1, 1, v2
	v_lshrrev_b32_e32 v3, 2, v2
	s_mul_hi_i32 s14, s51, s34
	s_add_u32 s28, s37, s15
	v_ashrrev_i16_sdwa v0, v205, sext(v0) dst_sel:DWORD dst_unused:UNUSED_PAD src0_sel:DWORD src1_sel:BYTE_0
	v_and_b32_e32 v1, 24, v1
	v_and_b32_e32 v3, 4, v3
	s_addc_u32 s29, s36, s14
	s_add_i32 s59, s58, 0
	v_bfe_i32 v17, v0, 0, 16
	v_or3_b32 v1, v4, v3, v1
	s_add_i32 m0, s59, 0x10000
	v_add_u32_e32 v0, v16, v17
	v_mul_lo_u32 v1, v1, s4
	global_load_lds_dwordx4 v140, s[28:29]
	s_add_i32 m0, s59, 0x12000
	v_add_lshl_u32 v144, v1, v0, 1
	s_add_u32 s14, s28, s44
	global_load_lds_dwordx4 v144, s[28:29]
	s_addc_u32 s15, s29, 0
	s_add_i32 m0, s59, 0x14000
	s_mul_i32 s18, s51, s26
	global_load_lds_dwordx4 v140, s[14:15]
	s_add_i32 m0, s59, 0x16000
	s_mul_hi_i32 s7, s51, s26
	s_add_u32 s30, s38, s18
	v_mov_b32_e32 v141, v48
	v_mov_b32_e32 v145, v48
	s_addc_u32 s31, s39, s7
	s_add_i32 s62, s59, 0x2000
	v_mul_lo_u32 v18, v2, s4
	v_lshl_add_u64 v[4:5], s[14:15], 0, v[140:141]
	v_lshl_add_u64 v[6:7], s[14:15], 0, v[144:145]
	global_load_lds_dwordx4 v144, s[14:15]
	s_mov_b32 m0, s59
	s_add_u32 s14, s30, s44
	v_add_lshl_u32 v142, v0, v18, 1
	global_load_lds_dwordx4 v138, s[30:31]
	s_mov_b32 m0, s62
	s_addc_u32 s15, s31, 0
	s_add_i32 s63, s59, 0x4000
	global_load_lds_dwordx4 v142, s[30:31]
	s_mov_b32 m0, s63
	s_add_i32 s64, s59, 0x6000
	global_load_lds_dwordx4 v138, s[14:15]
	s_mov_b32 m0, s64
	v_mov_b32_e32 v139, v48
	global_load_lds_dwordx4 v142, s[14:15]
	v_mov_b32_e32 v143, v48
	s_cmp_eq_u32 s6, 1
	v_lshl_add_u64 v[0:1], s[28:29], 0, v[140:141]
	v_lshl_add_u64 v[2:3], s[28:29], 0, v[144:145]
	v_lshl_add_u64 v[8:9], s[30:31], 0, v[138:139]
	v_lshl_add_u64 v[10:11], s[30:31], 0, v[142:143]
	s_cselect_b64 s[14:15], -1, 0
	s_cmp_lg_u32 s6, 1
	s_setprio 1
	s_cbranch_scc1 .LBB0_331
	s_setprio 2

; #define PG8_STAGE(bufoff, gbase, voff) do { _Pragma("unroll") for (int _i = 0; _i < 2; ++_i) \
;         __builtin_amdgcn_global_load_lds((const unsigned*)((const char*)(gbase) + (voff)[_i]), (PG8_LAS unsigned*)(lds + (bufoff) + ldsw + _i * 8192), 16, 0, 0); } while (0)
; #define PG8_LDA(dst, b, h) do { _Pragma("unroll") for (int m = 0; m < 4; ++m) _Pragma("unroll") for (int k = 0; k < 2; ++k) dst[m][k] = *(const PG8_LAS bf16x8*)(lds + PG8_SA(b, h) + aoff + m * 2048 + k * 1024); } while (0)
; #define PG8_LDB(dst, b, h) do { _Pragma("unroll") for (int n = 0; n < 2; ++n) _Pragma("unroll") for (int k = 0; k < 2; ++k) dst[n][k] = *(const PG8_LAS bf16x8*)(lds + PG8_SB(b, h) + boff + n * 2048 + k * 1024); } while (0)
; #define PG8_MMA(ai, bj, At, Bt) do { __builtin_amdgcn_s_setprio(1); _Pragma("unroll") for (int m = 0; m < 4; ++m) _Pragma("unroll") for (int n = 0; n < 2; ++n) _Pragma("unroll") for (int k = 0; k < 2; ++k) \
;         acc[ai][bj][m][n] = mma16<Epi::F16>(Bt[n][k], At[m][k], acc[ai][bj][m][n]); __builtin_amdgcn_s_setprio(0); } while (0)
; #define PG8_WAIT_V(n) asm volatile("s_waitcnt vmcnt(" #n ")" ::: "memory")
; #define PG8_WAIT_L(n) asm volatile("s_waitcnt lgkmcnt(" #n ")" ::: "memory")
; #define PG8_BAR __builtin_amdgcn_s_barrier()
; #define PG8_SCHED __builtin_amdgcn_sched_barrier(0)
; template <class Epi, class Sched, bool ALIGN_EPI = false, bool SP2 = false>
; __device__ __forceinline__ void gemm_phase(PG8_LAS unsigned char* lds, const Gemm g, const Sched& S, const Epi& E) {
;     ...
;             const bool last = (t == nt - 2);
;             const char* a1 = cA + (size_t)(t + 1) * kstep;
;             const char* a2 = last ? nA : cA + (size_t)(t + 2) * kstep; const char* b2 = last ? nB : cB + (size_t)(t + 2) * kstep;
;             const char* a3 = a2 + kstep; const char* b3 = b2 + kstep;
;             if (last && has_next) S.a_ready(nxt);
;             if constexpr (SP2) {
;             PG8_LDB(B0, 0, 0); PG8_LDB(B1, 0, 1); PG8_SCHED; PG8_LDA(At, 0, 0); PG8_STAGE(PG8_SA(1, 1), a1 + hstep, voffA);
;             PG8_WAIT_V(8); PG8_WAIT_L(0); PG8_BAR; PG8_MMA(0, 0, At, B0); PG8_MMA(0, 1, At, B1); PG8_BAR; PG8_SCHED;
.LBB0_347:
	s_add_i32 s31, s28, 2
	s_add_u32 s35, s4, 0x80
	s_addc_u32 s29, s5, 0
	s_add_i32 s73, 0, 0x10000
	s_cmp_eq_u32 s65, s28
	s_cselect_b32 s29, s23, s29
	s_cselect_b32 s28, s22, s35
	v_add_u32_e32 v49, s73, v191
	s_cselect_b32 vcc_hi, s25, s30
	s_cselect_b32 vcc_lo, s24, s27
	s_add_i32 s35, 0, 0x14000
	ds_read_b128 v[122:125], v49
	ds_read_b128 v[130:133], v49 offset:1024
	ds_read_b128 v[150:153], v49 offset:2048
	ds_read_b128 v[154:157], v49 offset:3072
	v_add_u32_e32 v49, s35, v191
	ds_read_b128 v[158:161], v49
	ds_read_b128 v[162:165], v49 offset:1024
	ds_read_b128 v[166:169], v49 offset:2048
	ds_read_b128 v[170:173], v49 offset:3072
	v_lshl_add_u64 v[182:183], s[4:5], 0, v[146:147]
	s_add_i32 m0, s59, 0xc000
	ds_read_b128 v[174:177], v192
	ds_read_b128 v[178:181], v192 offset:1024
	ds_read_b128 v[186:189], v192 offset:2048
	ds_read_b128 v[194:197], v192 offset:3072
	ds_read_b128 v[198:201], v192 offset:4096
	ds_read_b128 v[208:211], v192 offset:5120
	ds_read_b128 v[212:215], v192 offset:6144
	ds_read_b128 v[216:219], v192 offset:7168
	global_load_lds_dwordx4 v[182:183], off
	v_lshl_add_u64 v[182:183], s[4:5], 0, v[148:149]
	s_add_i32 m0, s59, 0xe000
	s_nop 0
	global_load_lds_dwordx4 v[182:183], off
	s_waitcnt vmcnt(8)
	s_waitcnt lgkmcnt(0)
	s_cmp_lg_u64 s[14:15], 0
	s_cbranch_scc0 .Lmy_b1_2_0
	s_barrier
.Lmy_b1_2_0:
	s_waitcnt lgkmcnt(0)
	v_mfma_f32_16x16x32_bf16 v[134:137], v[122:125], v[174:177], v[134:137]
	v_mfma_f32_16x16x32_bf16 v[126:129], v[150:153], v[174:177], v[126:129]
	v_mfma_f32_16x16x32_bf16 v[110:113], v[122:125], v[186:189], v[110:113]
	v_mfma_f32_16x16x32_bf16 v[106:109], v[150:153], v[186:189], v[106:109]
	v_mfma_f32_16x16x32_bf16 v[94:97], v[122:125], v[198:201], v[94:97]
	v_mfma_f32_16x16x32_bf16 v[90:93], v[150:153], v[198:201], v[90:93]
	v_mfma_f32_16x16x32_bf16 v[78:81], v[122:125], v[212:215], v[78:81]
	v_mfma_f32_16x16x32_bf16 v[74:77], v[150:153], v[212:215], v[74:77]
	v_mfma_f32_16x16x32_bf16 v[134:137], v[130:133], v[178:181], v[134:137]
	v_mfma_f32_16x16x32_bf16 v[126:129], v[154:157], v[178:181], v[126:129]
	v_mfma_f32_16x16x32_bf16 v[110:113], v[130:133], v[194:197], v[110:113]
	v_mfma_f32_16x16x32_bf16 v[106:109], v[154:157], v[194:197], v[106:109]
	v_mfma_f32_16x16x32_bf16 v[94:97], v[130:133], v[208:211], v[94:97]
	v_mfma_f32_16x16x32_bf16 v[90:93], v[154:157], v[208:211], v[90:93]
	v_mfma_f32_16x16x32_bf16 v[78:81], v[130:133], v[216:219], v[78:81]
	v_mfma_f32_16x16x32_bf16 v[74:77], v[154:157], v[216:219], v[74:77]
	v_mfma_f32_16x16x32_bf16 v[118:121], v[158:161], v[174:177], v[118:121]
	v_mfma_f32_16x16x32_bf16 v[114:117], v[166:169], v[174:177], v[114:117]
	v_mfma_f32_16x16x32_bf16 v[102:105], v[158:161], v[186:189], v[102:105]
	v_mfma_f32_16x16x32_bf16 v[98:101], v[166:169], v[186:189], v[98:101]
	v_mfma_f32_16x16x32_bf16 v[86:89], v[158:161], v[198:201], v[86:89]
	v_mfma_f32_16x16x32_bf16 v[82:85], v[166:169], v[198:201], v[82:85]
	v_mfma_f32_16x16x32_bf16 v[70:73], v[158:161], v[212:215], v[70:73]
	v_mfma_f32_16x16x32_bf16 v[66:69], v[166:169], v[212:215], v[66:69]
	v_mfma_f32_16x16x32_bf16 v[118:121], v[162:165], v[178:181], v[118:121]
	v_mfma_f32_16x16x32_bf16 v[114:117], v[170:173], v[178:181], v[114:117]
	v_mfma_f32_16x16x32_bf16 v[102:105], v[162:165], v[194:197], v[102:105]
	v_mfma_f32_16x16x32_bf16 v[98:101], v[170:173], v[194:197], v[98:101]
	v_mfma_f32_16x16x32_bf16 v[86:89], v[162:165], v[208:211], v[86:89]
	v_mfma_f32_16x16x32_bf16 v[82:85], v[170:173], v[208:211], v[82:85]
	v_mfma_f32_16x16x32_bf16 v[70:73], v[162:165], v[216:219], v[70:73]
	v_mfma_f32_16x16x32_bf16 v[66:69], v[170:173], v[216:219], v[66:69]
	s_cmp_lg_u64 s[14:15], 0
	s_cbranch_scc1 .Lmy_b2_2_0
	s_barrier
; #define PG8_STAGE(bufoff, gbase, voff) do { _Pragma("unroll") for (int _i = 0; _i < 2; ++_i) \
;         __builtin_amdgcn_global_load_lds((const unsigned*)((const char*)(gbase) + (voff)[_i]), (PG8_LAS unsigned*)(lds + (bufoff) + ldsw + _i * 8192), 16, 0, 0); } while (0)
; #define PG8_LDA(dst, b, h) do { _Pragma("unroll") for (int m = 0; m < 4; ++m) _Pragma("unroll") for (int k = 0; k < 2; ++k) dst[m][k] = *(const PG8_LAS bf16x8*)(lds + PG8_SA(b, h) + aoff + m * 2048 + k * 1024); } while (0)
; #define PG8_LDB(dst, b, h) do { _Pragma("unroll") for (int n = 0; n < 2; ++n) _Pragma("unroll") for (int k = 0; k < 2; ++k) dst[n][k] = *(const PG8_LAS bf16x8*)(lds + PG8_SB(b, h) + boff + n * 2048 + k * 1024); } while (0)
; #define PG8_MMA(ai, bj, At, Bt) do { __builtin_amdgcn_s_setprio(1); _Pragma("unroll") for (int m = 0; m < 4; ++m) _Pragma("unroll") for (int n = 0; n < 2; ++n) _Pragma("unroll") for (int k = 0; k < 2; ++k) \
;         acc[ai][bj][m][n] = mma16<Epi::F16>(Bt[n][k], At[m][k], acc[ai][bj][m][n]); __builtin_amdgcn_s_setprio(0); } while (0)
; #define PG8_WAIT_V(n) asm volatile("s_waitcnt vmcnt(" #n ")" ::: "memory")
; #define PG8_WAIT_L(n) asm volatile("s_waitcnt lgkmcnt(" #n ")" ::: "memory")
; #define PG8_BAR __builtin_amdgcn_s_barrier()
; #define PG8_SCHED __builtin_amdgcn_sched_barrier(0)
; template <class Epi, class Sched, bool ALIGN_EPI = false, bool SP2 = false>
; __device__ __forceinline__ void gemm_phase(PG8_LAS unsigned char* lds, const Gemm g, const Sched& S, const Epi& E) {
;     ...
;             PG8_LDA(At, 0, 1); PG8_STAGE(PG8_SB(0, 0), b2, voffB); PG8_STAGE(PG8_SB(0, 1), b2 + hstep, voffB); PG8_STAGE(PG8_SA(0, 0), a2, voffA);
;             PG8_WAIT_V(8); PG8_WAIT_L(0); PG8_BAR; PG8_MMA(1, 0, At, B0); PG8_MMA(1, 1, At, B1); PG8_BAR; PG8_SCHED;
;             PG8_LDB(B0, 1, 0); PG8_LDB(B1, 1, 1); PG8_SCHED; PG8_LDA(At, 1, 0); PG8_STAGE(PG8_SA(0, 1), a2 + hstep, voffA);
;             PG8_WAIT_V(8); PG8_WAIT_L(0); PG8_BAR; PG8_MMA(0, 0, At, B0); PG8_MMA(0, 1, At, B1); PG8_BAR; PG8_SCHED;
.Lmy_b2_2_0:
	s_add_i32 s73, s73, s58
	v_lshl_add_u64 v[182:183], vcc, 0, v[140:141]
	s_mov_b32 m0, s73
	ds_read_b128 v[174:177], v192 offset:16384
	ds_read_b128 v[178:181], v192 offset:17408
	ds_read_b128 v[186:189], v192 offset:18432
	ds_read_b128 v[194:197], v192 offset:19456
	ds_read_b128 v[198:201], v192 offset:20480
	ds_read_b128 v[208:211], v192 offset:21504
	ds_read_b128 v[212:215], v192 offset:22528
	ds_read_b128 v[216:219], v192 offset:23552
	global_load_lds_dwordx4 v[182:183], off
	s_add_i32 m0, s73, 0x2000
	v_lshl_add_u64 v[220:221], vcc, 0, v[144:145]
	s_add_u32 vcc_lo, vcc_lo, s44
	s_addc_u32 vcc_hi, vcc_hi, 0
	s_add_i32 s35, s35, s58
	global_load_lds_dwordx4 v[220:221], off
	v_lshl_add_u64 v[222:223], vcc, 0, v[140:141]
	s_mov_b32 m0, s35
	v_lshl_add_u64 v[224:225], vcc, 0, v[144:145]
	global_load_lds_dwordx4 v[222:223], off
	s_add_i32 m0, s35, 0x2000
	v_lshl_add_u64 v[226:227], s[28:29], 0, v[138:139]
	global_load_lds_dwordx4 v[224:225], off
	s_mov_b32 m0, s59
	v_lshl_add_u64 v[228:229], s[28:29], 0, v[142:143]
	global_load_lds_dwordx4 v[226:227], off
	s_mov_b32 m0, s62
	s_nop 0
	global_load_lds_dwordx4 v[228:229], off
	s_waitcnt vmcnt(8)
	s_waitcnt lgkmcnt(0)
	s_cmp_lg_u64 s[14:15], 0
	s_cbranch_scc0 .Lmy_b1_2_1
	s_barrier
.Lmy_b1_2_1:
	s_waitcnt lgkmcnt(0)
	v_mfma_f32_16x16x32_bf16 v[62:65], v[122:125], v[174:177], v[62:65]
	v_mfma_f32_16x16x32_bf16 v[58:61], v[150:153], v[174:177], v[58:61]
	v_mfma_f32_16x16x32_bf16 v[44:47], v[122:125], v[186:189], v[44:47]
	v_mfma_f32_16x16x32_bf16 v[40:43], v[150:153], v[186:189], v[40:43]
	v_mfma_f32_16x16x32_bf16 v[28:31], v[122:125], v[198:201], v[28:31]
	v_mfma_f32_16x16x32_bf16 v[24:27], v[150:153], v[198:201], v[24:27]
	v_mfma_f32_16x16x32_bf16 v[12:15], v[122:125], v[212:215], v[12:15]
	v_mfma_f32_16x16x32_bf16 v[8:11], v[150:153], v[212:215], v[8:11]
	v_mfma_f32_16x16x32_bf16 v[62:65], v[130:133], v[178:181], v[62:65]
	v_mfma_f32_16x16x32_bf16 v[58:61], v[154:157], v[178:181], v[58:61]
	v_mfma_f32_16x16x32_bf16 v[44:47], v[130:133], v[194:197], v[44:47]
	v_mfma_f32_16x16x32_bf16 v[40:43], v[154:157], v[194:197], v[40:43]
	v_mfma_f32_16x16x32_bf16 v[28:31], v[130:133], v[208:211], v[28:31]
	v_mfma_f32_16x16x32_bf16 v[24:27], v[154:157], v[208:211], v[24:27]
	v_mfma_f32_16x16x32_bf16 v[12:15], v[130:133], v[216:219], v[12:15]
	v_mfma_f32_16x16x32_bf16 v[8:11], v[154:157], v[216:219], v[8:11]
	v_mfma_f32_16x16x32_bf16 v[54:57], v[158:161], v[174:177], v[54:57]
	v_mfma_f32_16x16x32_bf16 v[50:53], v[166:169], v[174:177], v[50:53]
	v_mfma_f32_16x16x32_bf16 v[36:39], v[158:161], v[186:189], v[36:39]
	v_mfma_f32_16x16x32_bf16 v[32:35], v[166:169], v[186:189], v[32:35]
	v_mfma_f32_16x16x32_bf16 v[20:23], v[158:161], v[198:201], v[20:23]
	v_mfma_f32_16x16x32_bf16 v[16:19], v[166:169], v[198:201], v[16:19]
	v_mfma_f32_16x16x32_bf16 v[4:7], v[158:161], v[212:215], v[4:7]
	v_mfma_f32_16x16x32_bf16 v[0:3], v[166:169], v[212:215], v[0:3]
	v_mfma_f32_16x16x32_bf16 v[54:57], v[162:165], v[178:181], v[54:57]
	v_mfma_f32_16x16x32_bf16 v[50:53], v[170:173], v[178:181], v[50:53]
	v_mfma_f32_16x16x32_bf16 v[36:39], v[162:165], v[194:197], v[36:39]
	v_mfma_f32_16x16x32_bf16 v[32:35], v[170:173], v[194:197], v[32:35]
	v_mfma_f32_16x16x32_bf16 v[20:23], v[162:165], v[208:211], v[20:23]
	v_mfma_f32_16x16x32_bf16 v[16:19], v[170:173], v[208:211], v[16:19]
	v_mfma_f32_16x16x32_bf16 v[4:7], v[162:165], v[216:219], v[4:7]
	v_mfma_f32_16x16x32_bf16 v[0:3], v[170:173], v[216:219], v[0:3]
	s_cmp_lg_u64 s[14:15], 0
	s_cbranch_scc1 .Lmy_b2_2_1
	s_barrier
.Lmy_b2_2_1:
	s_add_i32 s35, 0, 0x18000
	v_add_u32_e32 v49, s35, v191
	s_add_i32 s73, 0, 0x1c000
	ds_read_b128 v[122:125], v49
	ds_read_b128 v[130:133], v49 offset:1024
	ds_read_b128 v[150:153], v49 offset:2048
	ds_read_b128 v[154:157], v49 offset:3072
	v_add_u32_e32 v49, s73, v191
	ds_read_b128 v[158:161], v49
	ds_read_b128 v[162:165], v49 offset:1024
	ds_read_b128 v[166:169], v49 offset:2048
	ds_read_b128 v[170:173], v49 offset:3072
	s_add_u32 s28, s28, s44
	s_addc_u32 s29, s29, 0
	s_mov_b32 m0, s63
	v_lshl_add_u64 v[230:231], s[28:29], 0, v[138:139]
	ds_read_b128 v[174:177], v192 offset:32768
	ds_read_b128 v[178:181], v192 offset:33792
	ds_read_b128 v[186:189], v192 offset:34816
	ds_read_b128 v[194:197], v192 offset:35840
	ds_read_b128 v[198:201], v192 offset:36864
	ds_read_b128 v[208:211], v192 offset:37888
	ds_read_b128 v[212:215], v192 offset:38912
	ds_read_b128 v[216:219], v192 offset:39936
	global_load_lds_dwordx4 v[230:231], off
	v_lshl_add_u64 v[230:231], s[28:29], 0, v[142:143]
	s_mov_b32 m0, s64
	s_nop 0
	global_load_lds_dwordx4 v[230:231], off
	s_waitcnt vmcnt(8)
	s_waitcnt lgkmcnt(0)
	s_cmp_lg_u64 s[14:15], 0
	s_cbranch_scc0 .Lmy_b1_2_2
	s_barrier

; #define PG8_STAGE(bufoff, gbase, voff) do { _Pragma("unroll") for (int _i = 0; _i < 2; ++_i) \
;         __builtin_amdgcn_global_load_lds((const unsigned*)((const char*)(gbase) + (voff)[_i]), (PG8_LAS unsigned*)(lds + (bufoff) + ldsw + _i * 8192), 16, 0, 0); } while (0)
; #define PG8_LDA(dst, b, h) do { _Pragma("unroll") for (int m = 0; m < 4; ++m) _Pragma("unroll") for (int k = 0; k < 2; ++k) dst[m][k] = *(const PG8_LAS bf16x8*)(lds + PG8_SA(b, h) + aoff + m * 2048 + k * 1024); } while (0)
; #define PG8_MMA(ai, bj, At, Bt) do { __builtin_amdgcn_s_setprio(1); _Pragma("unroll") for (int m = 0; m < 4; ++m) _Pragma("unroll") for (int n = 0; n < 2; ++n) _Pragma("unroll") for (int k = 0; k < 2; ++k) \
;         acc[ai][bj][m][n] = mma16<Epi::F16>(Bt[n][k], At[m][k], acc[ai][bj][m][n]); __builtin_amdgcn_s_setprio(0); } while (0)
; #define PG8_WAIT_V(n) asm volatile("s_waitcnt vmcnt(" #n ")" ::: "memory")
; #define PG8_WAIT_L(n) asm volatile("s_waitcnt lgkmcnt(" #n ")" ::: "memory")
; #define PG8_BAR __builtin_amdgcn_s_barrier()
; #define PG8_SCHED __builtin_amdgcn_sched_barrier(0)
; template <class Epi, class Sched, bool ALIGN_EPI = false, bool SP2 = false>
; __device__ __forceinline__ void gemm_phase(PG8_LAS unsigned char* lds, const Gemm g, const Sched& S, const Epi& E) {
;     ...
;             PG8_LDA(At, 1, 1); PG8_STAGE(PG8_SB(1, 0), b3, voffB); PG8_STAGE(PG8_SB(1, 1), b3 + hstep, voffB); PG8_STAGE(PG8_SA(1, 0), a3, voffA);
;             PG8_WAIT_V(8); PG8_WAIT_L(0); PG8_BAR; PG8_MMA(1, 0, At, B0); PG8_MMA(1, 1, At, B1); PG8_BAR; PG8_SCHED;
.Lmy_b2_2_2:
	s_add_i32 s28, s35, s58
	v_lshl_add_u64 v[182:183], v[182:183], 0, s[88:89]
	s_mov_b32 m0, s28
	ds_read_b128 v[174:177], v192 offset:49152
	ds_read_b128 v[178:181], v192 offset:50176
	ds_read_b128 v[186:189], v192 offset:51200
	ds_read_b128 v[194:197], v192 offset:52224
	ds_read_b128 v[198:201], v192 offset:53248
	ds_read_b128 v[208:211], v192 offset:54272
	ds_read_b128 v[212:215], v192 offset:55296
	ds_read_b128 v[216:219], v192 offset:56320
	global_load_lds_dwordx4 v[182:183], off
	v_lshl_add_u64 v[182:183], v[220:221], 0, s[88:89]
	s_add_i32 m0, s28, 0x2000
	s_add_i32 s28, s73, s58
	global_load_lds_dwordx4 v[182:183], off
	v_lshl_add_u64 v[182:183], v[222:223], 0, s[88:89]
	s_mov_b32 m0, s28
	s_nop 0
	global_load_lds_dwordx4 v[182:183], off
	v_lshl_add_u64 v[182:183], v[224:225], 0, s[88:89]
	s_add_i32 m0, s28, 0x2000
	s_nop 0
	global_load_lds_dwordx4 v[182:183], off
	v_lshl_add_u64 v[182:183], v[226:227], 0, s[88:89]
	s_mov_b32 m0, s98
	s_nop 0
	global_load_lds_dwordx4 v[182:183], off
	v_lshl_add_u64 v[182:183], v[228:229], 0, s[88:89]
	s_mov_b32 m0, s99
	s_nop 0
	global_load_lds_dwordx4 v[182:183], off
	s_waitcnt vmcnt(8)
	s_waitcnt lgkmcnt(0)
	s_cmp_lg_u64 s[14:15], 0
	s_cbranch_scc0 .Lmy_b1_2_3
	s_barrier

; #define PG8_WAIT_V(n) asm volatile("s_waitcnt vmcnt(" #n ")" ::: "memory")
; template <class Epi, class Sched, bool ALIGN_EPI = false, bool SP2 = false>
; __device__ __forceinline__ void gemm_phase(PG8_LAS unsigned char* lds, const Gemm g, const Sched& S, const Epi& E) {
;     ...
;         for (int t = 0; t < nt; t += 2) {
;             const bool last = (t == nt - 2);
;             const char* a1 = cA + (size_t)(t + 1) * kstep;
;             const char* a2 = last ? nA : cA + (size_t)(t + 2) * kstep; const char* b2 = last ? nB : cB + (size_t)(t + 2) * kstep;
;             const char* a3 = a2 + kstep; const char* b3 = b2 + kstep;
;             if (last && has_next) S.a_ready(nxt);
;             if constexpr (SP2) {
;             PG8_LDB(B0, 0, 0); PG8_LDB(B1, 0, 1); PG8_SCHED; PG8_LDA(At, 0, 0); PG8_STAGE(PG8_SA(1, 1), a1 + hstep, voffA);
;             PG8_WAIT_V(8); PG8_WAIT_L(0); PG8_BAR; PG8_MMA(0, 0, At, B0); PG8_MMA(0, 1, At, B1); PG8_BAR; PG8_SCHED;
;             PG8_LDA(At, 0, 1); PG8_STAGE(PG8_SB(0, 0), b2, voffB); PG8_STAGE(PG8_SB(0, 1), b2 + hstep, voffB); PG8_STAGE(PG8_SA(0, 0), a2, voffA);
;             PG8_WAIT_V(8); PG8_WAIT_L(0); PG8_BAR; PG8_MMA(1, 0, At, B0); PG8_MMA(1, 1, At, B1); PG8_BAR; PG8_SCHED;
;             PG8_LDB(B0, 1, 0); PG8_LDB(B1, 1, 1); PG8_SCHED; PG8_LDA(At, 1, 0); PG8_STAGE(PG8_SA(0, 1), a2 + hstep, voffA);
;             PG8_WAIT_V(8); PG8_WAIT_L(0); PG8_BAR; PG8_MMA(0, 0, At, B0); PG8_MMA(0, 1, At, B1); PG8_BAR; PG8_SCHED;
;             PG8_LDA(At, 1, 1); PG8_STAGE(PG8_SB(1, 0), b3, voffB); PG8_STAGE(PG8_SB(1, 1), b3 + hstep, voffB); PG8_STAGE(PG8_SA(1, 0), a3, voffA);
;             PG8_WAIT_V(8); PG8_WAIT_L(0); PG8_BAR; PG8_MMA(1, 0, At, B0); PG8_MMA(1, 1, At, B1); PG8_BAR; PG8_SCHED;
;             } else {
;             PG8_LDB(B0, 0, 0); PG8_SCHED; PG8_LDA(At, 0, 0); PG8_STAGE(PG8_SA(1, 1), a1 + hstep, voffA);
;             PG8_WAIT_L(8); PG8_BAR; PG8_WAIT_L(0); PG8_MMA(0, 0, At, B0); PG8_BAR; PG8_SCHED;
;             PG8_LDB(B1, 0, 1); PG8_STAGE(PG8_SB(0, 0), b2, voffB);
;             PG8_BAR; PG8_WAIT_L(0); PG8_MMA(0, 1, At, B1); PG8_BAR;
;             PG8_LDA(At, 0, 1); PG8_STAGE(PG8_SA(0, 0), a2, voffA);
;             PG8_BAR; PG8_WAIT_L(0); PG8_MMA(1, 0, At, B0); PG8_BAR; PG8_SCHED;
;             PG8_STAGE(PG8_SB(0, 1), b2 + hstep, voffB);
;             PG8_WAIT_V(6); PG8_BAR; PG8_MMA(1, 1, At, B1); PG8_BAR;
.Lmy_b2_2_3:
	s_add_u32 s4, s4, 0x100
	s_addc_u32 s5, s5, 0
	s_add_u32 s27, s27, 0x100
	s_addc_u32 s30, s30, 0
	s_cmp_ge_u32 s31, s76
	s_mov_b32 s28, s31
	s_cbranch_scc0 .LBB0_347
	s_and_b64 vcc, exec, s[16:17]
	s_cbranch_vccz .LBB0_350

; #define PG8_WAIT_V(n) asm volatile("s_waitcnt vmcnt(" #n ")" ::: "memory")
; #define PG8_BAR __builtin_amdgcn_s_barrier()
; template <class Epi, class Sched, bool ALIGN_EPI = false, bool SP2 = false>
; __device__ __forceinline__ void gemm_phase(PG8_LAS unsigned char* lds, const Gemm g, const Sched& S, const Epi& E) {
;     ...
;         if (!has_next) break;
; #pragma unroll
;         for (int a = 0; a < 2; ++a)
; #pragma unroll
;             for (int b = 0; b < 2; ++b)
; #pragma unroll
;                 for (int m = 0; m < 4; ++m)
; #pragma unroll
;                     for (int n = 0; n < 2; ++n) acc[a][b][m][n] = (f32x4){0.f, 0.f, 0.f, 0.f};
;         cur = nxt; cA = nA; cB = nB; ++ui;
;         if constexpr (ALIGN_EPI) { if (wr == 1) PG8_BAR; }
;     }
;     PG8_WAIT_V(0);
;     if constexpr (!ALIGN_EPI) { if (wr == 0) PG8_BAR; }
;     PG8_BAR;
.LBB0_505:
	s_and_b64 vcc, exec, s[6:7]
	s_mov_b64 s[4:5], -1
	s_cbranch_vccnz .LBB0_333
	s_andn2_b64 vcc, exec, s[14:15]
	s_cbranch_vccnz .LBB0_332
	s_branch .LBB0_332
.LBB0_508:
	s_waitcnt vmcnt(0)
	v_readlane_b32 s98, v242, 1
	v_readlane_b32 s96, v242, 3
	s_mov_b64 s[24:25], s[0:1]
	v_readlane_b32 s51, v242, 7
	v_readlane_b32 s76, v242, 10
	v_readlane_b32 s99, v242, 2
	v_readlane_b32 s97, v242, 4
	s_barrier
	s_setprio 0
